# sc1 write-through on every LN-phase row store (f32 16 B, bf16 8 B, fp8 4 B) in P1/P4/P10/P13 so those grid barriers find the L2 clean
# baseline (speedup 1.0000x reference)
.LBB0_131:
	v_add_f32_e32 v130, v126, v127
	v_add_f32_e32 v134, v128, v129
	v_add_f32_e32 v130, v130, v134
	v_add_f32_e32 v134, v122, v123
	v_add_f32_e32 v135, v124, v125
	v_add_f32_e32 v130, 0, v130
	v_add_f32_e32 v134, v134, v135
	v_add_f32_e32 v130, v134, v130
	v_add_f32_e32 v134, v118, v119
	v_add_f32_e32 v135, v120, v121
	v_add_f32_e32 v134, v134, v135
	v_add_f32_e32 v130, v134, v130
	v_add_f32_e32 v134, v114, v115
	v_add_f32_e32 v135, v116, v117
	v_add_f32_e32 v134, v134, v135
	v_add_f32_e32 v130, v134, v130
	v_add_f32_e32 v134, v110, v111
	v_add_f32_e32 v135, v112, v113
	v_add_f32_e32 v134, v134, v135
	v_add_f32_e32 v130, v134, v130
	v_add_f32_e32 v134, v106, v107
	v_add_f32_e32 v135, v108, v109
	v_add_f32_e32 v134, v134, v135
	v_add_f32_e32 v130, v134, v130
	v_add_f32_e32 v134, v102, v103
	v_add_f32_e32 v135, v104, v105
	v_add_f32_e32 v134, v134, v135
	v_add_f32_e32 v130, v134, v130
	v_add_f32_e32 v134, v98, v99
	v_add_f32_e32 v135, v100, v101
	v_add_f32_e32 v134, v134, v135
	v_add_f32_e32 v130, v134, v130
	v_add_f32_e32 v134, v30, v31
	v_add_f32_e32 v135, v32, v33
	v_add_f32_e32 v134, v134, v135
	v_add_f32_e32 v130, v134, v130
	v_add_f32_e32 v134, v26, v27
	v_add_f32_e32 v135, v28, v29
	v_add_f32_e32 v134, v134, v135
	v_add_f32_e32 v130, v134, v130
	v_add_f32_e32 v134, v22, v23
	v_add_f32_e32 v135, v24, v25
	v_add_f32_e32 v134, v134, v135
	v_add_f32_e32 v130, v134, v130
	v_add_f32_e32 v134, v18, v19
	v_add_f32_e32 v135, v20, v21
	v_add_f32_e32 v134, v134, v135
	v_add_f32_e32 v130, v134, v130
	v_add_f32_e32 v134, v14, v15
	v_add_f32_e32 v135, v16, v17
	v_add_f32_e32 v134, v134, v135
	v_add_f32_e32 v130, v134, v130
	v_add_f32_e32 v134, v10, v11
	v_add_f32_e32 v135, v12, v13
	v_add_f32_e32 v134, v134, v135
	v_add_f32_e32 v130, v134, v130
	v_add_f32_e32 v134, v6, v7
	v_add_f32_e32 v135, v8, v9
	v_add_f32_e32 v134, v134, v135
	v_add_f32_e32 v130, v134, v130
	v_add_f32_e32 v134, v2, v3
	v_add_f32_e32 v135, v4, v5
	v_add_f32_e32 v134, v134, v135
	v_add_f32_e32 v130, v134, v130
	v_and_b32_e32 v134, 64, v139
	v_add_u32_e32 v134, 64, v134
	v_xor_b32_e32 v135, 1, v139
	v_cmp_lt_i32_e32 vcc, v135, v134
	s_nop 1
	v_cndmask_b32_e32 v135, v139, v135, vcc
	v_lshlrev_b32_e32 v146, 2, v135
	ds_bpermute_b32 v135, v146, v130
	s_waitcnt lgkmcnt(0)
	v_add_f32_e32 v130, v130, v135
	v_xor_b32_e32 v135, 2, v139
	v_cmp_lt_i32_e32 vcc, v135, v134
	s_nop 1
	v_cndmask_b32_e32 v135, v139, v135, vcc
	v_lshlrev_b32_e32 v147, 2, v135
	ds_bpermute_b32 v135, v147, v130
	s_waitcnt lgkmcnt(0)
	v_add_f32_e32 v130, v130, v135
	v_xor_b32_e32 v135, 4, v139
	v_cmp_lt_i32_e32 vcc, v135, v134
	s_nop 1
	v_cndmask_b32_e32 v135, v139, v135, vcc
	v_lshlrev_b32_e32 v148, 2, v135
	ds_bpermute_b32 v135, v148, v130
	s_waitcnt lgkmcnt(0)
	v_add_f32_e32 v130, v130, v135
	v_xor_b32_e32 v135, 8, v139
	v_cmp_lt_i32_e32 vcc, v135, v134
	s_nop 1
	v_cndmask_b32_e32 v135, v139, v135, vcc
	v_lshlrev_b32_e32 v149, 2, v135
	ds_bpermute_b32 v135, v149, v130
	s_waitcnt lgkmcnt(0)
	v_add_f32_e32 v130, v130, v135
	v_xor_b32_e32 v135, 16, v139
	v_cmp_lt_i32_e32 vcc, v135, v134
	s_nop 1
	v_cndmask_b32_e32 v135, v139, v135, vcc
	v_lshlrev_b32_e32 v150, 2, v135
	ds_bpermute_b32 v135, v150, v130
	s_waitcnt lgkmcnt(0)
	v_add_f32_e32 v130, v130, v135
	v_xor_b32_e32 v135, 32, v139
	v_cmp_lt_i32_e32 vcc, v135, v134
	s_nop 1
	v_cndmask_b32_e32 v134, v139, v135, vcc
	v_lshlrev_b32_e32 v151, 2, v134
	ds_bpermute_b32 v134, v151, v130
	s_waitcnt lgkmcnt(0)
	v_add_f32_e32 v152, v130, v134
	v_fmamk_f32 v127, v152, 0xb9800000, v127
	v_fmamk_f32 v126, v152, 0xb9800000, v126
	v_fmamk_f32 v129, v152, 0xb9800000, v129
	v_fmac_f32_e32 v128, 0xb9800000, v152
	v_pk_mul_f32 v[134:135], v[128:129], v[128:129]
	v_pk_mul_f32 v[140:141], v[126:127], v[126:127]
	v_fmamk_f32 v125, v152, 0xb9800000, v125
	v_pk_mov_b32 v[142:143], v[140:141], v[134:135] op_sel:[1,0]
	v_mov_b32_e32 v141, v135
	v_pk_add_f32 v[134:135], v[142:143], v[140:141]
	v_fmac_f32_e32 v124, 0xb9800000, v152
	v_pk_add_f32 v[140:141], v[134:135], v[134:135] op_sel_hi:[0,1]
	v_fmamk_f32 v135, v152, 0xb9800000, v123
	v_fmamk_f32 v134, v152, 0xb9800000, v122
	v_pk_mul_f32 v[122:123], v[124:125], v[124:125]
	v_pk_mul_f32 v[142:143], v[134:135], v[134:135]
	v_fmac_f32_e32 v120, 0xb9800000, v152
	v_pk_mov_b32 v[144:145], v[142:143], v[122:123] op_sel:[1,0]
	v_mov_b32_e32 v143, v123
	v_pk_add_f32 v[122:123], v[144:145], v[142:143]
	v_fmamk_f32 v121, v152, 0xb9800000, v121
	v_pk_add_f32 v[142:143], v[122:123], v[122:123] op_sel_hi:[0,1]
	v_fmamk_f32 v122, v152, 0xb9800000, v118
	v_fmamk_f32 v123, v152, 0xb9800000, v119
	v_mul_f32_e32 v118, v122, v122
	v_pk_fma_f32 v[118:119], v[122:123], v[122:123], v[118:119] op_sel_hi:[1,1,0]
	v_fmamk_f32 v117, v152, 0xb9800000, v117
	v_mul_f32_e32 v118, v120, v120
	v_pk_fma_f32 v[144:145], v[120:121], v[120:121], v[118:119] op_sel_hi:[1,1,0]
	v_fmamk_f32 v116, v152, 0xb9800000, v116
	v_fmamk_f32 v115, v152, 0xb9800000, v115
	v_fmac_f32_e32 v114, 0xb9800000, v152
	v_mul_f32_e32 v118, v114, v114
	v_mul_f32_e32 v144, v115, v115
	v_mul_f32_e32 v140, v116, v116
	v_mul_f32_e32 v142, v117, v117
	v_pk_add_f32 v[118:119], v[118:119], v[144:145]
	v_pk_add_f32 v[140:141], v[140:141], v[142:143]
	v_fmamk_f32 v113, v152, 0xb9800000, v113
	v_pk_add_f32 v[118:119], v[118:119], v[140:141]
	v_fmac_f32_e32 v112, 0xb9800000, v152
	v_pk_add_f32 v[140:141], v[118:119], v[118:119] op_sel_hi:[0,1]
	v_fmamk_f32 v119, v152, 0xb9800000, v111
	v_fmamk_f32 v118, v152, 0xb9800000, v110
	v_pk_mul_f32 v[110:111], v[112:113], v[112:113]
	v_pk_mul_f32 v[142:143], v[118:119], v[118:119]
	v_fmac_f32_e32 v108, 0xb9800000, v152
	v_pk_mov_b32 v[144:145], v[142:143], v[110:111] op_sel:[1,0]
	v_mov_b32_e32 v143, v111
	v_pk_add_f32 v[110:111], v[144:145], v[142:143]
	v_fmamk_f32 v109, v152, 0xb9800000, v109
	v_pk_add_f32 v[142:143], v[110:111], v[110:111] op_sel_hi:[0,1]
	v_fmamk_f32 v110, v152, 0xb9800000, v106
	v_fmamk_f32 v111, v152, 0xb9800000, v107
	v_mul_f32_e32 v106, v110, v110
	v_pk_fma_f32 v[106:107], v[110:111], v[110:111], v[106:107] op_sel_hi:[1,1,0]
	v_fmamk_f32 v105, v152, 0xb9800000, v105
	v_mul_f32_e32 v106, v108, v108
	v_pk_fma_f32 v[144:145], v[108:109], v[108:109], v[106:107] op_sel_hi:[1,1,0]
	v_fmamk_f32 v104, v152, 0xb9800000, v104
	v_fmamk_f32 v103, v152, 0xb9800000, v103
	v_fmac_f32_e32 v102, 0xb9800000, v152
	v_mul_f32_e32 v106, v102, v102
	v_mul_f32_e32 v144, v103, v103
	v_mul_f32_e32 v142, v104, v104
	v_mul_f32_e32 v140, v105, v105
	v_pk_add_f32 v[106:107], v[106:107], v[144:145]
	v_pk_add_f32 v[140:141], v[142:143], v[140:141]
	v_fmamk_f32 v99, v152, 0xb9800000, v99
	v_fmamk_f32 v98, v152, 0xb9800000, v98
	v_fmamk_f32 v101, v152, 0xb9800000, v101
	v_fmac_f32_e32 v100, 0xb9800000, v152
	v_pk_add_f32 v[106:107], v[106:107], v[140:141]
	v_pk_mul_f32 v[140:141], v[100:101], v[100:101]
	v_pk_mul_f32 v[142:143], v[98:99], v[98:99]
	v_fmamk_f32 v30, v152, 0xb9800000, v30
	v_pk_mov_b32 v[144:145], v[142:143], v[140:141] op_sel:[1,0]
	v_mov_b32_e32 v143, v141
	v_fmamk_f32 v31, v152, 0xb9800000, v31
	v_fmac_f32_e32 v32, 0xb9800000, v152
	v_mul_f32_e32 v130, v30, v30
	v_pk_add_f32 v[140:141], v[144:145], v[142:143]
	v_fmamk_f32 v33, v152, 0xb9800000, v33
	v_pk_fma_f32 v[142:143], v[30:31], v[30:31], v[130:131] op_sel_hi:[1,1,0]
	v_mul_f32_e32 v130, v32, v32
	v_pk_fma_f32 v[144:145], v[32:33], v[32:33], v[130:131] op_sel_hi:[1,1,0]
	v_fmamk_f32 v27, v152, 0xb9800000, v27
	v_fmac_f32_e32 v26, 0xb9800000, v152
	v_pk_add_f32 v[106:107], v[106:107], v[106:107] op_sel_hi:[0,1]
	v_pk_add_f32 v[140:141], v[140:141], v[140:141] op_sel_hi:[0,1]
	v_fmamk_f32 v29, v152, 0xb9800000, v29
	v_fmamk_f32 v28, v152, 0xb9800000, v28
	v_mul_f32_e32 v142, v26, v26
	v_mul_f32_e32 v144, v27, v27
	v_mul_f32_e32 v140, v28, v28
	v_mul_f32_e32 v106, v29, v29
	v_pk_add_f32 v[142:143], v[142:143], v[144:145]
	v_pk_add_f32 v[106:107], v[140:141], v[106:107]
	v_fmamk_f32 v23, v152, 0xb9800000, v23
	v_fmamk_f32 v22, v152, 0xb9800000, v22
	v_fmamk_f32 v25, v152, 0xb9800000, v25
	v_fmac_f32_e32 v24, 0xb9800000, v152
	v_pk_add_f32 v[106:107], v[142:143], v[106:107]
	v_pk_mul_f32 v[140:141], v[24:25], v[24:25]
	v_pk_mul_f32 v[142:143], v[22:23], v[22:23]
	v_fmamk_f32 v18, v152, 0xb9800000, v18
	v_pk_mov_b32 v[144:145], v[142:143], v[140:141] op_sel:[1,0]
	v_mov_b32_e32 v143, v141
	v_fmamk_f32 v19, v152, 0xb9800000, v19
	v_fmac_f32_e32 v20, 0xb9800000, v152
	v_mul_f32_e32 v130, v18, v18
	v_pk_add_f32 v[140:141], v[144:145], v[142:143]
	v_fmamk_f32 v21, v152, 0xb9800000, v21
	v_pk_fma_f32 v[142:143], v[18:19], v[18:19], v[130:131] op_sel_hi:[1,1,0]
	v_mul_f32_e32 v130, v20, v20
	v_pk_fma_f32 v[144:145], v[20:21], v[20:21], v[130:131] op_sel_hi:[1,1,0]
	v_fmamk_f32 v15, v152, 0xb9800000, v15
	v_fmac_f32_e32 v14, 0xb9800000, v152
	v_pk_add_f32 v[106:107], v[106:107], v[106:107] op_sel_hi:[0,1]
	v_pk_add_f32 v[140:141], v[140:141], v[140:141] op_sel_hi:[0,1]
	v_fmamk_f32 v17, v152, 0xb9800000, v17
	v_fmamk_f32 v16, v152, 0xb9800000, v16
	v_mul_f32_e32 v142, v14, v14
	v_mul_f32_e32 v144, v15, v15
	v_mul_f32_e32 v140, v16, v16
	v_mul_f32_e32 v106, v17, v17
	v_pk_add_f32 v[142:143], v[142:143], v[144:145]
	v_pk_add_f32 v[106:107], v[140:141], v[106:107]
	v_fmamk_f32 v11, v152, 0xb9800000, v11
	v_fmamk_f32 v10, v152, 0xb9800000, v10
	v_fmamk_f32 v13, v152, 0xb9800000, v13
	v_fmac_f32_e32 v12, 0xb9800000, v152
	v_pk_add_f32 v[106:107], v[142:143], v[106:107]
	v_pk_mul_f32 v[140:141], v[12:13], v[12:13]
	v_pk_mul_f32 v[142:143], v[10:11], v[10:11]
	v_fmamk_f32 v6, v152, 0xb9800000, v6
	v_pk_mov_b32 v[144:145], v[142:143], v[140:141] op_sel:[1,0]
	v_mov_b32_e32 v143, v141
	v_fmamk_f32 v7, v152, 0xb9800000, v7
	v_fmac_f32_e32 v8, 0xb9800000, v152
	v_mul_f32_e32 v130, v6, v6
	v_pk_add_f32 v[140:141], v[144:145], v[142:143]
	v_fmamk_f32 v9, v152, 0xb9800000, v9
	v_pk_fma_f32 v[142:143], v[6:7], v[6:7], v[130:131] op_sel_hi:[1,1,0]
	v_mul_f32_e32 v130, v8, v8
	v_pk_fma_f32 v[144:145], v[8:9], v[8:9], v[130:131] op_sel_hi:[1,1,0]
	v_fmamk_f32 v3, v152, 0xb9800000, v3
	v_fmac_f32_e32 v2, 0xb9800000, v152
	v_fmamk_f32 v5, v152, 0xb9800000, v5
	v_fmamk_f32 v4, v152, 0xb9800000, v4
	v_pk_add_f32 v[106:107], v[106:107], v[106:107] op_sel_hi:[0,1]
	v_pk_add_f32 v[140:141], v[140:141], v[140:141] op_sel_hi:[0,1]
	v_mul_f32_e32 v142, v2, v2
	v_mul_f32_e32 v144, v3, v3
	v_mul_f32_e32 v140, v4, v4
	v_mul_f32_e32 v106, v5, v5
	v_pk_add_f32 v[142:143], v[142:143], v[144:145]
	v_pk_add_f32 v[106:107], v[140:141], v[106:107]
	s_nop 0
	v_pk_add_f32 v[106:107], v[142:143], v[106:107]
	s_nop 0
	v_add_f32_e32 v106, v106, v107
	ds_bpermute_b32 v107, v146, v106
	s_waitcnt lgkmcnt(0)
	v_add_f32_e32 v106, v106, v107
	ds_bpermute_b32 v107, v147, v106
	s_waitcnt lgkmcnt(0)
	v_add_f32_e32 v106, v106, v107
	ds_bpermute_b32 v107, v148, v106
	s_waitcnt lgkmcnt(0)
	v_add_f32_e32 v106, v106, v107
	ds_bpermute_b32 v107, v149, v106
	s_waitcnt lgkmcnt(0)
	v_add_f32_e32 v106, v106, v107
	ds_bpermute_b32 v107, v150, v106
	s_waitcnt lgkmcnt(0)
	v_add_f32_e32 v106, v106, v107
	ds_bpermute_b32 v107, v151, v106
	s_waitcnt lgkmcnt(0)
	v_add_f32_e32 v106, v106, v107
	v_fmamk_f32 v106, v106, 0x39800000, v137
	v_mul_f32_e32 v107, 0x4f800000, v106
	v_cmp_gt_f32_e32 vcc, s12, v106
	s_nop 1
	v_cndmask_b32_e32 v106, v106, v107, vcc
	v_sqrt_f32_e32 v107, v106
	s_nop 0
	v_add_u32_e32 v130, -1, v107
	v_fma_f32 v140, -v130, v107, v106
	v_cmp_ge_f32_e64 s[0:1], 0, v140
	v_add_u32_e32 v140, 1, v107
	s_nop 0
	v_cndmask_b32_e64 v130, v107, v130, s[0:1]
	v_fma_f32 v107, -v140, v107, v106
	v_cmp_lt_f32_e64 s[0:1], 0, v107
	s_nop 1
	v_cndmask_b32_e64 v107, v130, v140, s[0:1]
	v_mul_f32_e32 v130, 0x37800000, v107
	v_cndmask_b32_e32 v107, v107, v130, vcc
	v_cmp_class_f32_e32 vcc, v106, v138
	s_nop 1
	v_cndmask_b32_e32 v106, v107, v106, vcc
	v_div_scale_f32 v107, s[0:1], v106, v106, 1.0
	v_rcp_f32_e32 v130, v107
	s_and_b32 s0, s6, 0xffff8000
	s_add_i32 s0, s0, 0xfffc8000
	s_cmpk_gt_i32 s8, 0x1fff
	v_fma_f32 v140, -v107, v130, 1.0
	v_fmac_f32_e32 v130, v140, v130
	v_div_scale_f32 v140, vcc, 1.0, v106, 1.0
	v_mul_f32_e32 v141, v140, v130
	v_fma_f32 v142, -v107, v141, v140
	v_fmac_f32_e32 v141, v142, v130
	v_fma_f32 v107, -v107, v141, v140
	s_cselect_b32 s0, s0, 0
	v_div_fmas_f32 v107, v107, v130, v141
	v_add_u32_e32 v130, s0, v136
	ds_read_b128 v[140:143], v130 offset:49152
	ds_read_b128 v[144:147], v130 offset:32768
	ds_read_b128 v[148:151], v130 offset:50176
	v_div_fixup_f32 v106, v107, v106, 1.0
	v_pk_mul_f32 v[128:129], v[128:129], v[106:107] op_sel_hi:[1,0]
	v_pk_mul_f32 v[126:127], v[126:127], v[106:107] op_sel_hi:[1,0]
	s_waitcnt lgkmcnt(2)
	v_pk_add_f32 v[152:153], v[142:143], 1.0 op_sel_hi:[1,0]
	v_pk_add_f32 v[154:155], v[140:141], 1.0 op_sel_hi:[1,0]
	ds_read_b128 v[140:143], v130 offset:33792
	s_waitcnt lgkmcnt(2)
	v_pk_fma_f32 v[128:129], v[152:153], v[128:129], v[146:147]
	v_pk_fma_f32 v[152:153], v[154:155], v[126:127], v[144:145]
	v_pk_mul_f32 v[124:125], v[124:125], v[106:107] op_sel_hi:[1,0]
	s_waitcnt lgkmcnt(1)
	v_pk_add_f32 v[126:127], v[150:151], 1.0 op_sel_hi:[1,0]
	v_pk_add_f32 v[144:145], v[148:149], 1.0 op_sel_hi:[1,0]
	s_waitcnt lgkmcnt(0)
	v_pk_fma_f32 v[148:149], v[126:127], v[124:125], v[142:143]
	v_pk_mul_f32 v[134:135], v[134:135], v[106:107] op_sel_hi:[1,0]
	ds_read_b128 v[124:127], v130 offset:51200
	v_pk_fma_f32 v[134:135], v[144:145], v[134:135], v[140:141]
	ds_read_b128 v[140:143], v130 offset:52224
	ds_read_b128 v[144:147], v130 offset:34816
	v_pk_mul_f32 v[120:121], v[120:121], v[106:107] op_sel_hi:[1,0]
	v_pk_mul_f32 v[122:123], v[122:123], v[106:107] op_sel_hi:[1,0]
	v_mov_b32_e32 v107, 0
	v_cvt_pk_fp8_f32 v107, v152, v153
	s_waitcnt lgkmcnt(2)
	v_pk_add_f32 v[154:155], v[124:125], 1.0 op_sel_hi:[1,0]
	v_pk_add_f32 v[150:151], v[126:127], 1.0 op_sel_hi:[1,0]
	s_waitcnt lgkmcnt(0)
	v_pk_fma_f32 v[122:123], v[154:155], v[122:123], v[144:145]
	v_mov_b32_e32 v144, 0
	v_cvt_pk_fp8_f32 v144, v134, v135
	v_mov_b32_e32 v134, 0
	ds_read_b128 v[124:127], v130 offset:35840
	v_cvt_pk_fp8_f32 v134, v122, v123
	v_cvt_pk_fp8_f32 v107, v128, v129 op_sel:[0,0,1]
	v_pk_fma_f32 v[120:121], v[150:151], v[120:121], v[146:147]
	v_cvt_pk_fp8_f32 v144, v148, v149 op_sel:[0,0,1]
	v_cvt_pk_fp8_f32 v134, v120, v121 op_sel:[0,0,1]
	v_pk_mul_f32 v[114:115], v[114:115], v[106:107] op_sel_hi:[1,0]
	v_pk_add_f32 v[120:121], v[140:141], 1.0 op_sel_hi:[1,0]
	v_pk_mul_f32 v[118:119], v[118:119], v[106:107] op_sel_hi:[1,0]
	s_waitcnt lgkmcnt(0)
	v_pk_fma_f32 v[114:115], v[120:121], v[114:115], v[124:125]
	v_mov_b32_e32 v120, 0
	v_cvt_pk_fp8_f32 v120, v114, v115
	v_pk_mul_f32 v[114:115], v[116:117], v[106:107] op_sel_hi:[1,0]
	v_pk_add_f32 v[116:117], v[142:143], 1.0 op_sel_hi:[1,0]
	s_add_i32 s6, s6, s7
	v_pk_fma_f32 v[114:115], v[116:117], v[114:115], v[126:127]
	s_andn2_b64 vcc, exec, s[4:5]
	v_cvt_pk_fp8_f32 v120, v114, v115 op_sel:[0,0,1]
	global_store_dword v[132:133], v107, off sc1
	global_store_dword v[132:133], v144, off offset:256 sc1
	global_store_dword v[132:133], v134, off offset:512 sc1
	global_store_dword v[132:133], v120, off offset:768 sc1
	ds_read_b128 v[114:117], v130 offset:53248
	ds_read_b128 v[120:123], v130 offset:36864
	v_mov_b32_e32 v107, 0
	ds_read_b128 v[124:127], v130 offset:54272
	ds_read_b128 v[140:143], v130 offset:37888
	s_waitcnt lgkmcnt(3)
	v_pk_add_f32 v[114:115], v[114:115], 1.0 op_sel_hi:[1,0]
	s_mov_b32 s8, s13
	s_waitcnt lgkmcnt(2)
	v_pk_fma_f32 v[114:115], v[114:115], v[118:119], v[120:121]
	s_nop 0
	v_cvt_pk_fp8_f32 v107, v114, v115
	v_pk_add_f32 v[114:115], v[116:117], 1.0 op_sel_hi:[1,0]
	ds_read_b128 v[116:119], v130 offset:56320
	v_pk_mul_f32 v[112:113], v[112:113], v[106:107] op_sel_hi:[1,0]
	s_nop 0
	v_pk_fma_f32 v[112:113], v[114:115], v[112:113], v[122:123]
	ds_read_b128 v[120:123], v130 offset:39936
	v_cvt_pk_fp8_f32 v107, v112, v113 op_sel:[0,0,1]
	s_waitcnt lgkmcnt(3)
	v_pk_add_f32 v[112:113], v[124:125], 1.0 op_sel_hi:[1,0]
	v_mov_b32_e32 v124, 0
	v_pk_mul_f32 v[110:111], v[110:111], v[106:107] op_sel_hi:[1,0]
	s_waitcnt lgkmcnt(2)
	v_pk_fma_f32 v[110:111], v[112:113], v[110:111], v[140:141]
	v_pk_mul_f32 v[108:109], v[108:109], v[106:107] op_sel_hi:[1,0]
	v_cvt_pk_fp8_f32 v124, v110, v111
	v_pk_add_f32 v[110:111], v[126:127], 1.0 op_sel_hi:[1,0]
	v_pk_mul_f32 v[102:103], v[102:103], v[106:107] op_sel_hi:[1,0]
	v_pk_fma_f32 v[112:113], v[110:111], v[108:109], v[142:143]
	ds_read_b128 v[108:111], v130 offset:55296
	v_cvt_pk_fp8_f32 v124, v112, v113 op_sel:[0,0,1]
	ds_read_b128 v[112:115], v130 offset:38912
	v_pk_mul_f32 v[98:99], v[98:99], v[106:107] op_sel_hi:[1,0]
	v_pk_mul_f32 v[30:31], v[30:31], v[106:107] op_sel_hi:[1,0]
	s_waitcnt lgkmcnt(1)
	v_pk_add_f32 v[108:109], v[108:109], 1.0 op_sel_hi:[1,0]
	s_waitcnt vmcnt(19)
	v_mov_b64_e32 v[128:129], v[48:49]
	s_waitcnt lgkmcnt(0)
	v_pk_fma_f32 v[102:103], v[102:103], v[108:109], v[112:113]
	v_mov_b32_e32 v108, 0
	v_cvt_pk_fp8_f32 v108, v102, v103
	v_pk_mul_f32 v[102:103], v[104:105], v[106:107] op_sel_hi:[1,0]
	v_pk_add_f32 v[104:105], v[110:111], 1.0 op_sel_hi:[1,0]
	v_mov_b64_e32 v[126:127], v[46:47]
	v_pk_fma_f32 v[102:103], v[102:103], v[104:105], v[114:115]
	s_nop 0
	v_cvt_pk_fp8_f32 v108, v102, v103 op_sel:[0,0,1]
	v_pk_add_f32 v[102:103], v[116:117], 1.0 op_sel_hi:[1,0]
	s_nop 0
	v_pk_fma_f32 v[98:99], v[98:99], v[102:103], v[120:121]
	v_mov_b32_e32 v102, 0
	v_cvt_pk_fp8_f32 v102, v98, v99
	v_pk_mul_f32 v[98:99], v[100:101], v[106:107] op_sel_hi:[1,0]
	v_pk_add_f32 v[100:101], v[118:119], 1.0 op_sel_hi:[1,0]
	s_waitcnt vmcnt(17)
	v_mov_b64_e32 v[120:121], v[40:41]
	v_pk_fma_f32 v[98:99], v[98:99], v[100:101], v[122:123]
	v_mov_b64_e32 v[118:119], v[38:39]
	v_cvt_pk_fp8_f32 v102, v98, v99 op_sel:[0,0,1]
	global_store_dword v[132:133], v107, off offset:1024 sc1
	global_store_dword v[132:133], v124, off offset:1280 sc1
	global_store_dword v[132:133], v108, off offset:1536 sc1
	global_store_dword v[132:133], v102, off offset:1792 sc1
	ds_read_b128 v[98:101], v130 offset:57344
	ds_read_b128 v[102:105], v130 offset:40960
	v_mov_b32_e32 v107, 0
	ds_read_b128 v[108:111], v130 offset:58368
	ds_read_b128 v[112:115], v130 offset:41984
	s_waitcnt lgkmcnt(3)
	v_pk_add_f32 v[98:99], v[98:99], 1.0 op_sel_hi:[1,0]
	v_mov_b64_e32 v[124:125], v[44:45]
	s_waitcnt lgkmcnt(2)
	v_pk_fma_f32 v[30:31], v[30:31], v[98:99], v[102:103]
	v_mov_b64_e32 v[122:123], v[42:43]
	v_cvt_pk_fp8_f32 v107, v30, v31
	v_pk_mul_f32 v[30:31], v[32:33], v[106:107] op_sel_hi:[1,0]
	v_pk_add_f32 v[32:33], v[100:101], 1.0 op_sel_hi:[1,0]
	ds_read_b128 v[98:101], v130 offset:60416
	v_pk_fma_f32 v[30:31], v[30:31], v[32:33], v[104:105]
	ds_read_b128 v[102:105], v130 offset:44032
	v_cvt_pk_fp8_f32 v107, v30, v31 op_sel:[0,0,1]
	s_waitcnt lgkmcnt(3)
	v_pk_add_f32 v[30:31], v[108:109], 1.0 op_sel_hi:[1,0]
	v_mov_b32_e32 v108, 0
	v_pk_mul_f32 v[26:27], v[26:27], v[106:107] op_sel_hi:[1,0]
	s_waitcnt lgkmcnt(2)
	v_pk_fma_f32 v[26:27], v[26:27], v[30:31], v[112:113]
	v_pk_mul_f32 v[28:29], v[28:29], v[106:107] op_sel_hi:[1,0]
	v_cvt_pk_fp8_f32 v108, v26, v27
	v_pk_add_f32 v[26:27], v[110:111], 1.0 op_sel_hi:[1,0]
	v_pk_mul_f32 v[22:23], v[22:23], v[106:107] op_sel_hi:[1,0]
	v_pk_fma_f32 v[30:31], v[28:29], v[26:27], v[114:115]
	ds_read_b128 v[26:29], v130 offset:59392
	v_cvt_pk_fp8_f32 v108, v30, v31 op_sel:[0,0,1]
	ds_read_b128 v[30:33], v130 offset:43008
	v_pk_mul_f32 v[18:19], v[18:19], v[106:107] op_sel_hi:[1,0]
	v_pk_mul_f32 v[14:15], v[14:15], v[106:107] op_sel_hi:[1,0]
	s_waitcnt lgkmcnt(1)
	v_pk_add_f32 v[26:27], v[26:27], 1.0 op_sel_hi:[1,0]
	v_pk_mul_f32 v[10:11], v[10:11], v[106:107] op_sel_hi:[1,0]
	s_waitcnt lgkmcnt(0)
	v_pk_fma_f32 v[22:23], v[22:23], v[26:27], v[30:31]
	v_mov_b32_e32 v26, 0
	v_cvt_pk_fp8_f32 v26, v22, v23
	v_pk_mul_f32 v[22:23], v[24:25], v[106:107] op_sel_hi:[1,0]
	v_pk_add_f32 v[24:25], v[28:29], 1.0 op_sel_hi:[1,0]
	v_pk_mul_f32 v[12:13], v[12:13], v[106:107] op_sel_hi:[1,0]
	v_pk_fma_f32 v[22:23], v[22:23], v[24:25], v[32:33]
	v_pk_mul_f32 v[6:7], v[6:7], v[106:107] op_sel_hi:[1,0]
	v_cvt_pk_fp8_f32 v26, v22, v23 op_sel:[0,0,1]
	v_pk_add_f32 v[22:23], v[98:99], 1.0 op_sel_hi:[1,0]
	v_mov_b32_e32 v98, 0
	v_pk_fma_f32 v[18:19], v[18:19], v[22:23], v[102:103]
	v_mov_b32_e32 v22, 0
	v_cvt_pk_fp8_f32 v22, v18, v19
	v_pk_mul_f32 v[18:19], v[20:21], v[106:107] op_sel_hi:[1,0]
	v_pk_add_f32 v[20:21], v[100:101], 1.0 op_sel_hi:[1,0]
	v_pk_mul_f32 v[2:3], v[2:3], v[106:107] op_sel_hi:[1,0]
	v_pk_fma_f32 v[18:19], v[18:19], v[20:21], v[104:105]
	s_waitcnt vmcnt(20)
	v_mov_b64_e32 v[116:117], v[36:37]
	v_cvt_pk_fp8_f32 v22, v18, v19 op_sel:[0,0,1]
	global_store_dword v[132:133], v107, off offset:2048 sc1
	global_store_dword v[132:133], v108, off offset:2304 sc1
	global_store_dword v[132:133], v26, off offset:2560 sc1
	global_store_dword v[132:133], v22, off offset:2816 sc1
	ds_read_b128 v[18:21], v130 offset:61440
	ds_read_b128 v[22:25], v130 offset:45056
	ds_read_b128 v[26:29], v130 offset:62464
	ds_read_b128 v[30:33], v130 offset:46080
	s_waitcnt vmcnt(23)
	v_mov_b64_e32 v[112:113], v[64:65]
	s_waitcnt lgkmcnt(3)
	v_pk_add_f32 v[18:19], v[18:19], 1.0 op_sel_hi:[1,0]
	s_waitcnt vmcnt(21)
	v_mov_b64_e32 v[104:105], v[56:57]
	s_waitcnt lgkmcnt(2)
	v_pk_fma_f32 v[14:15], v[14:15], v[18:19], v[22:23]
	v_mov_b64_e32 v[114:115], v[34:35]
	v_cvt_pk_fp8_f32 v98, v14, v15
	v_pk_mul_f32 v[14:15], v[16:17], v[106:107] op_sel_hi:[1,0]
	v_pk_add_f32 v[16:17], v[20:21], 1.0 op_sel_hi:[1,0]
	ds_read_b128 v[18:21], v130 offset:64512
	v_pk_fma_f32 v[14:15], v[14:15], v[16:17], v[24:25]
	ds_read_b128 v[22:25], v130 offset:48128
	v_cvt_pk_fp8_f32 v98, v14, v15 op_sel:[0,0,1]
	s_waitcnt lgkmcnt(3)
	v_pk_add_f32 v[14:15], v[26:27], 1.0 op_sel_hi:[1,0]
	v_mov_b32_e32 v26, 0
	s_waitcnt lgkmcnt(2)
	v_pk_fma_f32 v[10:11], v[10:11], v[14:15], v[30:31]
	v_mov_b64_e32 v[110:111], v[62:63]
	v_cvt_pk_fp8_f32 v26, v10, v11
	v_pk_add_f32 v[10:11], v[28:29], 1.0 op_sel_hi:[1,0]
	v_mov_b64_e32 v[102:103], v[54:55]
	v_pk_fma_f32 v[14:15], v[12:13], v[10:11], v[32:33]
	ds_read_b128 v[10:13], v130 offset:63488
	v_cvt_pk_fp8_f32 v26, v14, v15 op_sel:[0,0,1]
	ds_read_b128 v[14:17], v130 offset:47104
	s_waitcnt vmcnt(19)
	v_mov_b64_e32 v[30:31], v[78:79]
	v_mov_b64_e32 v[32:33], v[80:81]
	s_waitcnt lgkmcnt(1)
	v_pk_add_f32 v[10:11], v[10:11], 1.0 op_sel_hi:[1,0]
	s_waitcnt lgkmcnt(0)
	v_pk_fma_f32 v[6:7], v[6:7], v[10:11], v[14:15]
	v_mov_b32_e32 v10, 0
	v_cvt_pk_fp8_f32 v10, v6, v7
	v_pk_mul_f32 v[6:7], v[8:9], v[106:107] op_sel_hi:[1,0]
	v_pk_add_f32 v[8:9], v[12:13], 1.0 op_sel_hi:[1,0]
	s_nop 0
	v_pk_fma_f32 v[6:7], v[6:7], v[8:9], v[16:17]
	s_waitcnt vmcnt(15)
	v_mov_b64_e32 v[14:15], v[94:95]
	v_cvt_pk_fp8_f32 v10, v6, v7 op_sel:[0,0,1]
	v_pk_add_f32 v[6:7], v[18:19], 1.0 op_sel_hi:[1,0]
	v_mov_b64_e32 v[16:17], v[96:97]
	v_pk_fma_f32 v[2:3], v[2:3], v[6:7], v[22:23]
	v_mov_b32_e32 v6, 0
	v_cvt_pk_fp8_f32 v6, v2, v3
	v_pk_mul_f32 v[2:3], v[4:5], v[106:107] op_sel_hi:[1,0]
	v_pk_add_f32 v[4:5], v[20:21], 1.0 op_sel_hi:[1,0]
	v_mov_b64_e32 v[108:109], v[60:61]
	v_pk_fma_f32 v[2:3], v[2:3], v[4:5], v[24:25]
	v_mov_b64_e32 v[22:23], v[70:71]
	v_cvt_pk_fp8_f32 v6, v2, v3 op_sel:[0,0,1]
	global_store_dword v[132:133], v98, off offset:3072 sc1
	global_store_dword v[132:133], v26, off offset:3328 sc1
	global_store_dword v[132:133], v10, off offset:3584 sc1
	global_store_dword v[132:133], v6, off offset:3840 sc1
	v_mov_b64_e32 v[100:101], v[52:53]
	v_mov_b64_e32 v[26:27], v[74:75]
	v_mov_b64_e32 v[18:19], v[66:67]
	s_waitcnt vmcnt(18)
	v_mov_b64_e32 v[10:11], v[90:91]
	s_waitcnt vmcnt(17)
	v_mov_b64_e32 v[6:7], v[86:87]
	s_waitcnt vmcnt(16)
	v_mov_b64_e32 v[2:3], v[82:83]
	v_lshl_add_u64 v[132:133], v[132:133], 0, s[2:3]
	v_mov_b64_e32 v[106:107], v[58:59]
	v_mov_b64_e32 v[98:99], v[50:51]
	v_mov_b64_e32 v[28:29], v[76:77]
	v_mov_b64_e32 v[24:25], v[72:73]
	v_mov_b64_e32 v[20:21], v[68:69]
	v_mov_b64_e32 v[12:13], v[92:93]
	v_mov_b64_e32 v[8:9], v[88:89]
	v_mov_b64_e32 v[4:5], v[84:85]
	s_cbranch_vccz .LBB0_134

.LBB0_359:
	v_add_f32_e32 v130, v126, v127
	v_add_f32_e32 v131, v128, v129
	v_add_f32_e32 v130, v130, v131
	v_and_b32_e32 v131, 64, v243
	v_add_u32_e32 v131, 64, v131
	v_xor_b32_e32 v132, 1, v243
	v_cmp_lt_i32_e32 vcc, v132, v131
	v_add_f32_e32 v130, v244, v130
	v_lshlrev_b32_e32 v192, 4, v1
	v_cndmask_b32_e32 v132, v243, v132, vcc
	v_lshlrev_b32_e32 v202, 2, v132
	ds_bpermute_b32 v132, v202, v130
	s_and_b32 s2, s69, 0xffff8000
	s_add_i32 s2, s2, 0x8000
	s_waitcnt lgkmcnt(0)
	v_add_f32_e32 v130, v130, v132
	v_xor_b32_e32 v132, 2, v243
	v_cmp_lt_i32_e32 vcc, v132, v131
	s_nop 1
	v_cndmask_b32_e32 v132, v243, v132, vcc
	v_lshlrev_b32_e32 v203, 2, v132
	ds_bpermute_b32 v132, v203, v130
	s_waitcnt lgkmcnt(0)
	v_add_f32_e32 v130, v130, v132
	v_xor_b32_e32 v132, 4, v243
	v_cmp_lt_i32_e32 vcc, v132, v131
	s_nop 1
	v_cndmask_b32_e32 v132, v243, v132, vcc
	v_lshlrev_b32_e32 v204, 2, v132
	ds_bpermute_b32 v132, v204, v130
	s_waitcnt lgkmcnt(0)
	v_add_f32_e32 v130, v130, v132
	v_xor_b32_e32 v132, 8, v243
	v_cmp_lt_i32_e32 vcc, v132, v131
	s_nop 1
	v_cndmask_b32_e32 v132, v243, v132, vcc
	v_lshlrev_b32_e32 v205, 2, v132
	ds_bpermute_b32 v132, v205, v130
	s_waitcnt lgkmcnt(0)
	v_add_f32_e32 v130, v130, v132
	v_xor_b32_e32 v132, 16, v243
	v_cmp_lt_i32_e32 vcc, v132, v131
	s_nop 1
	v_cndmask_b32_e32 v132, v243, v132, vcc
	v_lshlrev_b32_e32 v206, 2, v132
	ds_bpermute_b32 v132, v206, v130
	s_waitcnt lgkmcnt(0)
	v_add_f32_e32 v130, v130, v132
	v_xor_b32_e32 v132, 32, v243
	v_cmp_lt_i32_e32 vcc, v132, v131
	s_nop 1
	v_cndmask_b32_e32 v131, v243, v132, vcc
	v_lshlrev_b32_e32 v207, 2, v131
	ds_bpermute_b32 v131, v207, v130
	s_waitcnt lgkmcnt(0)
	v_add_f32_e32 v144, v130, v131
	v_fmamk_f32 v143, v144, 0xb9800000, v87
	v_fmamk_f32 v142, v144, 0xb9800000, v86
	v_fmamk_f32 v89, v144, 0xb9800000, v89
	v_fmac_f32_e32 v88, 0xb9800000, v144
	v_pk_mul_f32 v[86:87], v[88:89], v[88:89]
	v_pk_mul_f32 v[130:131], v[142:143], v[142:143]
	v_fmamk_f32 v141, v144, 0xb9800000, v79
	v_pk_mov_b32 v[132:133], v[130:131], v[86:87] op_sel:[1,0]
	v_mov_b32_e32 v131, v87
	v_fmamk_f32 v140, v144, 0xb9800000, v78
	v_fmamk_f32 v81, v144, 0xb9800000, v81
	v_fmac_f32_e32 v80, 0xb9800000, v144
	v_fmamk_f32 v138, v144, 0xb9800000, v74
	v_pk_add_f32 v[86:87], v[132:133], v[130:131]
	v_pk_mul_f32 v[78:79], v[80:81], v[80:81]
	v_pk_mul_f32 v[130:131], v[140:141], v[140:141]
	v_fmamk_f32 v139, v144, 0xb9800000, v75
	v_mul_f32_e32 v74, v138, v138
	v_pk_mov_b32 v[132:133], v[130:131], v[78:79] op_sel:[1,0]
	v_mov_b32_e32 v131, v79
	v_fmac_f32_e32 v76, 0xb9800000, v144
	v_pk_fma_f32 v[74:75], v[138:139], v[138:139], v[74:75] op_sel_hi:[1,1,0]
	v_pk_add_f32 v[78:79], v[132:133], v[130:131]
	v_fmamk_f32 v77, v144, 0xb9800000, v77
	v_mul_f32_e32 v74, v76, v76
	v_pk_add_f32 v[86:87], v[86:87], v[86:87] op_sel_hi:[0,1]
	v_pk_add_f32 v[78:79], v[78:79], v[78:79] op_sel_hi:[0,1]
	v_pk_fma_f32 v[130:131], v[76:77], v[76:77], v[74:75] op_sel_hi:[1,1,0]
	v_fmamk_f32 v137, v144, 0xb9800000, v85
	v_fmamk_f32 v136, v144, 0xb9800000, v84
	v_fmamk_f32 v83, v144, 0xb9800000, v83
	v_fmac_f32_e32 v82, 0xb9800000, v144
	v_mul_f32_e32 v74, v82, v82
	v_mul_f32_e32 v130, v83, v83
	v_mul_f32_e32 v86, v136, v136
	v_mul_f32_e32 v78, v137, v137
	v_pk_add_f32 v[74:75], v[74:75], v[130:131]
	v_pk_add_f32 v[78:79], v[86:87], v[78:79]
	v_fmamk_f32 v135, v144, 0xb9800000, v71
	v_fmamk_f32 v134, v144, 0xb9800000, v70
	v_fmamk_f32 v73, v144, 0xb9800000, v73
	v_fmac_f32_e32 v72, 0xb9800000, v144
	v_fmamk_f32 v132, v144, 0xb9800000, v66
	v_pk_add_f32 v[74:75], v[74:75], v[78:79]
	v_pk_mul_f32 v[70:71], v[72:73], v[72:73]
	v_pk_mul_f32 v[78:79], v[134:135], v[134:135]
	v_fmamk_f32 v133, v144, 0xb9800000, v67
	v_mul_f32_e32 v66, v132, v132
	v_pk_mov_b32 v[84:85], v[78:79], v[70:71] op_sel:[1,0]
	v_mov_b32_e32 v79, v71
	v_fmac_f32_e32 v68, 0xb9800000, v144
	v_pk_fma_f32 v[66:67], v[132:133], v[132:133], v[66:67] op_sel_hi:[1,1,0]
	v_pk_add_f32 v[70:71], v[84:85], v[78:79]
	v_fmamk_f32 v69, v144, 0xb9800000, v69
	v_mul_f32_e32 v66, v68, v68
	v_pk_add_f32 v[74:75], v[74:75], v[74:75] op_sel_hi:[0,1]
	v_pk_add_f32 v[70:71], v[70:71], v[70:71] op_sel_hi:[0,1]
	v_pk_fma_f32 v[78:79], v[68:69], v[68:69], v[66:67] op_sel_hi:[1,1,0]
	v_fmamk_f32 v131, v144, 0xb9800000, v93
	v_fmamk_f32 v130, v144, 0xb9800000, v92
	v_fmamk_f32 v91, v144, 0xb9800000, v91
	v_fmac_f32_e32 v90, 0xb9800000, v144
	v_mul_f32_e32 v66, v90, v90
	v_mul_f32_e32 v78, v91, v91
	v_mul_f32_e32 v70, v130, v130
	v_mul_f32_e32 v74, v131, v131
	v_pk_add_f32 v[66:67], v[66:67], v[78:79]
	v_pk_add_f32 v[70:71], v[70:71], v[74:75]
	v_fmamk_f32 v201, v144, 0xb9800000, v95
	v_pk_add_f32 v[66:67], v[66:67], v[70:71]
	v_fmamk_f32 v200, v144, 0xb9800000, v94
	v_fmamk_f32 v97, v144, 0xb9800000, v97
	v_fmac_f32_e32 v96, 0xb9800000, v144
	v_pk_add_f32 v[66:67], v[66:67], v[66:67] op_sel_hi:[0,1]
	v_pk_mul_f32 v[70:71], v[96:97], v[96:97]
	v_pk_mul_f32 v[74:75], v[200:201], v[200:201]
	v_fmamk_f32 v94, v144, 0xb9800000, v98
	v_pk_mov_b32 v[78:79], v[74:75], v[70:71] op_sel:[1,0]
	v_mov_b32_e32 v75, v71
	v_fmamk_f32 v95, v144, 0xb9800000, v99
	v_fmac_f32_e32 v100, 0xb9800000, v144
	v_mul_f32_e32 v66, v94, v94
	v_pk_add_f32 v[70:71], v[78:79], v[74:75]
	v_fmamk_f32 v101, v144, 0xb9800000, v101
	v_pk_fma_f32 v[74:75], v[94:95], v[94:95], v[66:67] op_sel_hi:[1,1,0]
	v_mul_f32_e32 v66, v100, v100
	v_pk_add_f32 v[70:71], v[70:71], v[70:71] op_sel_hi:[0,1]
	v_pk_fma_f32 v[78:79], v[100:101], v[100:101], v[66:67] op_sel_hi:[1,1,0]
	v_fmamk_f32 v93, v144, 0xb9800000, v113
	v_fmamk_f32 v92, v144, 0xb9800000, v112
	v_fmamk_f32 v111, v144, 0xb9800000, v111
	v_fmac_f32_e32 v110, 0xb9800000, v144
	v_mul_f32_e32 v74, v110, v110
	v_mul_f32_e32 v78, v111, v111
	v_mul_f32_e32 v70, v92, v92
	v_mul_f32_e32 v66, v93, v93
	v_pk_add_f32 v[74:75], v[74:75], v[78:79]
	v_pk_add_f32 v[66:67], v[70:71], v[66:67]
	v_fmamk_f32 v87, v144, 0xb9800000, v107
	v_pk_add_f32 v[66:67], v[74:75], v[66:67]
	v_fmamk_f32 v86, v144, 0xb9800000, v106
	v_fmamk_f32 v109, v144, 0xb9800000, v109
	v_fmac_f32_e32 v108, 0xb9800000, v144
	v_pk_add_f32 v[66:67], v[66:67], v[66:67] op_sel_hi:[0,1]
	v_pk_mul_f32 v[70:71], v[108:109], v[108:109]
	v_pk_mul_f32 v[74:75], v[86:87], v[86:87]
	v_fmamk_f32 v84, v144, 0xb9800000, v102
	v_pk_mov_b32 v[78:79], v[74:75], v[70:71] op_sel:[1,0]
	v_mov_b32_e32 v75, v71
	v_fmamk_f32 v85, v144, 0xb9800000, v103
	v_fmac_f32_e32 v104, 0xb9800000, v144
	v_mul_f32_e32 v66, v84, v84
	v_pk_add_f32 v[70:71], v[78:79], v[74:75]
	v_fmamk_f32 v105, v144, 0xb9800000, v105
	v_pk_fma_f32 v[74:75], v[84:85], v[84:85], v[66:67] op_sel_hi:[1,1,0]
	v_mul_f32_e32 v66, v104, v104
	v_pk_add_f32 v[70:71], v[70:71], v[70:71] op_sel_hi:[0,1]
	v_pk_fma_f32 v[98:99], v[104:105], v[104:105], v[66:67] op_sel_hi:[1,1,0]
	v_fmamk_f32 v79, v144, 0xb9800000, v125
	v_fmamk_f32 v78, v144, 0xb9800000, v124
	v_fmamk_f32 v123, v144, 0xb9800000, v123
	v_fmac_f32_e32 v122, 0xb9800000, v144
	v_mul_f32_e32 v74, v122, v122
	v_mul_f32_e32 v98, v123, v123
	v_mul_f32_e32 v70, v78, v78
	v_mul_f32_e32 v66, v79, v79
	v_pk_add_f32 v[74:75], v[74:75], v[98:99]
	v_pk_add_f32 v[66:67], v[70:71], v[66:67]
	v_fmamk_f32 v117, v144, 0xb9800000, v117
	v_pk_add_f32 v[66:67], v[74:75], v[66:67]
	v_fmamk_f32 v75, v144, 0xb9800000, v115
	v_fmamk_f32 v74, v144, 0xb9800000, v114
	v_fmac_f32_e32 v116, 0xb9800000, v144
	v_pk_add_f32 v[98:99], v[66:67], v[66:67] op_sel_hi:[0,1]
	v_pk_mul_f32 v[66:67], v[116:117], v[116:117]
	v_pk_mul_f32 v[70:71], v[74:75], v[74:75]
	v_fmac_f32_e32 v120, 0xb9800000, v144
	v_pk_mov_b32 v[102:103], v[70:71], v[66:67] op_sel:[1,0]
	v_mov_b32_e32 v71, v67
	v_pk_add_f32 v[66:67], v[102:103], v[70:71]
	v_fmamk_f32 v70, v144, 0xb9800000, v118
	v_pk_add_f32 v[102:103], v[66:67], v[66:67] op_sel_hi:[0,1]
	v_fmamk_f32 v71, v144, 0xb9800000, v119
	v_mul_f32_e32 v66, v70, v70
	v_fmamk_f32 v121, v144, 0xb9800000, v121
	v_pk_fma_f32 v[106:107], v[70:71], v[70:71], v[66:67] op_sel_hi:[1,1,0]
	v_mul_f32_e32 v66, v120, v120
	v_pk_fma_f32 v[112:113], v[120:121], v[120:121], v[66:67] op_sel_hi:[1,1,0]
	v_fmamk_f32 v67, v144, 0xb9800000, v129
	v_fmamk_f32 v66, v144, 0xb9800000, v128
	v_fmamk_f32 v127, v144, 0xb9800000, v127
	v_fmac_f32_e32 v126, 0xb9800000, v144
	v_mul_f32_e32 v106, v126, v126
	v_mul_f32_e32 v112, v127, v127
	v_mul_f32_e32 v102, v66, v66
	v_mul_f32_e32 v98, v67, v67
	v_pk_add_f32 v[106:107], v[106:107], v[112:113]
	v_pk_add_f32 v[98:99], v[102:103], v[98:99]
	ds_read_b128 v[112:115], v241
	ds_read_b128 v[144:147], v241 offset:16384
	v_pk_add_f32 v[98:99], v[106:107], v[98:99]
	ds_read_b128 v[148:151], v241 offset:17408
	ds_read_b128 v[208:211], v241 offset:1024
	v_add_f32_e32 v98, v98, v99
	ds_bpermute_b32 v99, v202, v98
	s_waitcnt lgkmcnt(0)
	v_add_f32_e32 v98, v98, v99
	ds_bpermute_b32 v99, v203, v98
	s_waitcnt lgkmcnt(0)
	v_add_f32_e32 v98, v98, v99
	ds_bpermute_b32 v99, v204, v98
	s_waitcnt lgkmcnt(0)
	v_add_f32_e32 v98, v98, v99
	ds_bpermute_b32 v99, v205, v98
	s_waitcnt lgkmcnt(0)
	v_add_f32_e32 v98, v98, v99
	ds_bpermute_b32 v99, v206, v98
	s_waitcnt lgkmcnt(0)
	v_add_f32_e32 v98, v98, v99
	ds_bpermute_b32 v99, v207, v98
	s_waitcnt lgkmcnt(0)
	v_add_f32_e32 v98, v98, v99
	v_fmamk_f32 v98, v98, 0x39800000, v179
	v_mul_f32_e32 v99, 0x4f800000, v98
	v_cmp_gt_f32_e32 vcc, s79, v98
	s_nop 1
	v_cndmask_b32_e32 v98, v98, v99, vcc
	v_sqrt_f32_e32 v99, v98
	s_nop 0
	v_add_u32_e32 v102, -1, v99
	v_fma_f32 v103, -v102, v99, v98
	v_cmp_ge_f32_e64 s[0:1], 0, v103
	v_add_u32_e32 v103, 1, v99
	s_nop 0
	v_cndmask_b32_e64 v102, v99, v102, s[0:1]
	v_fma_f32 v99, -v103, v99, v98
	v_cmp_lt_f32_e64 s[0:1], 0, v99
	s_nop 1
	v_cndmask_b32_e64 v99, v102, v103, s[0:1]
	v_mul_f32_e32 v102, 0x37800000, v99
	v_cndmask_b32_e32 v99, v99, v102, vcc
	v_cmp_class_f32_e32 vcc, v98, v242
	s_nop 1
	v_cndmask_b32_e32 v98, v99, v98, vcc
	v_div_scale_f32 v99, s[0:1], v98, v98, 1.0
	v_rcp_f32_e32 v102, v99
	s_nop 0
	v_fma_f32 v103, -v99, v102, 1.0
	v_fmac_f32_e32 v102, v103, v102
	v_div_scale_f32 v103, vcc, 1.0, v98, 1.0
	v_mul_f32_e32 v106, v103, v102
	v_fma_f32 v107, -v99, v106, v103
	v_fmac_f32_e32 v106, v107, v102
	v_fma_f32 v99, -v99, v106, v103
	v_div_fmas_f32 v99, v99, v102, v106
	v_div_fixup_f32 v102, v99, v98, 1.0
	v_pk_mul_f32 v[88:89], v[88:89], v[102:103] op_sel_hi:[1,0]
	v_pk_mul_f32 v[106:107], v[142:143], v[102:103] op_sel_hi:[1,0]
	v_pk_fma_f32 v[154:155], v[114:115], v[88:89], v[146:147]
	v_pk_fma_f32 v[152:153], v[112:113], v[106:107], v[144:145]
	v_mov_b32_e32 v107, v155
	v_pk_mov_b32 v[88:89], v[152:153], v[154:155] op_sel:[1,0]
	v_mov_b32_e32 v106, v152
	v_pk_add_f32 v[88:89], v[88:89], v[106:107]
	v_pk_mul_f32 v[80:81], v[80:81], v[102:103] op_sel_hi:[1,0]
	v_pk_mul_f32 v[106:107], v[140:141], v[102:103] op_sel_hi:[1,0]
	v_pk_fma_f32 v[150:151], v[210:211], v[80:81], v[150:151]
	v_pk_fma_f32 v[148:149], v[208:209], v[106:107], v[148:149]
	global_store_dwordx4 v192, v[152:155], s[54:55] sc1 nt
	global_store_dwordx4 v192, v[148:151], s[54:55] offset:1024 sc1 nt
	ds_read_b128 v[112:115], v241 offset:18432
	ds_read_b128 v[140:143], v241 offset:2048
	ds_read_b128 v[208:211], v241 offset:19456
	ds_read_b128 v[212:215], v241 offset:3072
	v_pk_mov_b32 v[80:81], v[148:149], v[150:151] op_sel:[1,0]
	v_mov_b32_e32 v106, v148
	v_mov_b32_e32 v107, v151
	v_pk_add_f32 v[80:81], v[80:81], v[106:107]
	v_pk_mul_f32 v[106:107], v[138:139], v[102:103] op_sel_hi:[1,0]
	v_pk_mul_f32 v[76:77], v[76:77], v[102:103] op_sel_hi:[1,0]
	s_waitcnt lgkmcnt(2)
	v_pk_fma_f32 v[144:145], v[140:141], v[106:107], v[112:113]
	v_pk_mul_f32 v[82:83], v[82:83], v[102:103] op_sel_hi:[1,0]
	v_pk_mul_f32 v[112:113], v[136:137], v[102:103] op_sel_hi:[1,0]
	v_add_f32_e32 v88, v88, v89
	v_pk_add_f32 v[80:81], v[80:81], v[80:81] op_sel_hi:[0,1]
	v_pk_fma_f32 v[146:147], v[142:143], v[76:77], v[114:115]
	s_waitcnt lgkmcnt(0)
	v_pk_fma_f32 v[142:143], v[214:215], v[112:113], v[210:211]
	v_pk_fma_f32 v[140:141], v[212:213], v[82:83], v[208:209]
	v_add_f32_e32 v89, 0, v88
	global_store_dwordx4 v192, v[144:147], s[54:55] offset:2048 sc1 nt
	v_add_f32_e32 v77, v144, v145
	v_add_f32_e32 v107, v146, v147
	global_store_dwordx4 v192, v[140:143], s[54:55] offset:3072 sc1 nt
	v_mov_b32_e32 v76, v140
	v_mov_b32_e32 v106, v141
	v_mov_b32_e32 v80, v142
	v_mov_b32_e32 v88, v143
	v_pk_add_f32 v[76:77], v[76:77], v[106:107]
	v_pk_add_f32 v[80:81], v[80:81], v[88:89]
	v_pk_mul_f32 v[88:89], v[134:135], v[102:103] op_sel_hi:[1,0]
	v_pk_add_f32 v[76:77], v[76:77], v[80:81]
	ds_read_b128 v[80:83], v241 offset:4096
	ds_read_b128 v[112:115], v241 offset:20480
	v_pk_mul_f32 v[72:73], v[72:73], v[102:103] op_sel_hi:[1,0]
	ds_read_b128 v[208:211], v241 offset:21504
	ds_read_b128 v[212:215], v241 offset:5120
	v_lshl_add_u64 v[98:99], s[54:55], 0, v[192:193]
	v_pk_mul_f32 v[68:69], v[68:69], v[102:103] op_sel_hi:[1,0]
	s_waitcnt lgkmcnt(2)
	v_pk_fma_f32 v[138:139], v[82:83], v[72:73], v[114:115]
	v_pk_fma_f32 v[136:137], v[80:81], v[88:89], v[112:113]
	v_add_co_u32_e32 v72, vcc, s77, v98
	v_pk_mov_b32 v[80:81], v[136:137], v[138:139] op_sel:[1,0]
	v_mov_b32_e32 v82, v136
	v_mov_b32_e32 v83, v139
	v_addc_co_u32_e32 v73, vcc, 0, v99, vcc
	v_pk_add_f32 v[80:81], v[80:81], v[82:83]
	v_add_co_u32_e32 v118, vcc, s75, v98
	v_pk_add_f32 v[106:107], v[80:81], v[80:81] op_sel_hi:[0,1]
	v_pk_mul_f32 v[80:81], v[132:133], v[102:103] op_sel_hi:[1,0]
	v_addc_co_u32_e32 v119, vcc, 0, v99, vcc
	s_waitcnt lgkmcnt(0)
	v_pk_fma_f32 v[134:135], v[214:215], v[68:69], v[210:211]
	v_pk_fma_f32 v[132:133], v[212:213], v[80:81], v[208:209]
	global_store_dwordx4 v[118:119], v[136:139], off offset:-4096 sc1 nt
	global_store_dwordx4 v[72:73], v[132:135], off offset:1024 sc1 nt
	ds_read_b128 v[80:83], v241 offset:22528
	ds_read_b128 v[112:115], v241 offset:6144
	v_pk_mul_f32 v[128:129], v[90:91], v[102:103] op_sel_hi:[1,0]
	v_pk_mul_f32 v[130:131], v[130:131], v[102:103] op_sel_hi:[1,0]
	ds_read_b128 v[88:91], v241 offset:23552
	ds_read_b128 v[208:211], v241 offset:7168
	v_pk_add_f32 v[76:77], v[76:77], v[76:77] op_sel_hi:[0,1]
	s_waitcnt lgkmcnt(2)
	v_pk_fma_f32 v[130:131], v[114:115], v[130:131], v[82:83]
	v_pk_fma_f32 v[128:129], v[112:113], v[128:129], v[80:81]
	v_add_f32_e32 v69, v132, v133
	v_add_f32_e32 v125, v134, v135
	v_mov_b32_e32 v68, v128
	v_mov_b32_e32 v124, v129
	v_mov_b32_e32 v106, v130
	v_mov_b32_e32 v76, v131
	v_pk_add_f32 v[68:69], v[68:69], v[124:125]
	v_pk_add_f32 v[76:77], v[106:107], v[76:77]
	v_pk_mul_f32 v[80:81], v[96:97], v[102:103] op_sel_hi:[1,0]
	v_pk_add_f32 v[68:69], v[68:69], v[76:77]
	v_pk_mul_f32 v[76:77], v[200:201], v[102:103] op_sel_hi:[1,0]
	s_waitcnt lgkmcnt(0)
	v_pk_fma_f32 v[114:115], v[210:211], v[80:81], v[90:91]
	v_pk_fma_f32 v[112:113], v[208:209], v[76:77], v[88:89]
	global_store_dwordx4 v[72:73], v[128:131], off offset:2048 sc1 nt
	global_store_dwordx4 v[72:73], v[112:115], off offset:3072 sc1 nt
	ds_read_b128 v[80:83], v241 offset:8192
	ds_read_b128 v[88:91], v241 offset:24576
	ds_read_b128 v[208:211], v241 offset:25600
	ds_read_b128 v[212:215], v241 offset:9216
	v_pk_mov_b32 v[72:73], v[112:113], v[114:115] op_sel:[1,0]
	v_mov_b32_e32 v76, v112
	v_mov_b32_e32 v77, v115
	v_pk_add_f32 v[72:73], v[72:73], v[76:77]
	v_pk_mul_f32 v[76:77], v[94:95], v[102:103] op_sel_hi:[1,0]
	v_pk_mul_f32 v[94:95], v[100:101], v[102:103] op_sel_hi:[1,0]
	v_pk_add_f32 v[68:69], v[68:69], v[68:69] op_sel_hi:[0,1]
	s_waitcnt lgkmcnt(2)
	v_pk_fma_f32 v[96:97], v[82:83], v[94:95], v[90:91]
	v_pk_fma_f32 v[94:95], v[80:81], v[76:77], v[88:89]
	v_pk_mul_f32 v[82:83], v[110:111], v[102:103] op_sel_hi:[1,0]
	v_pk_mul_f32 v[88:89], v[92:93], v[102:103] op_sel_hi:[1,0]
	s_waitcnt lgkmcnt(0)
	v_pk_fma_f32 v[90:91], v[212:213], v[82:83], v[208:209]
	v_pk_fma_f32 v[92:93], v[214:215], v[88:89], v[210:211]
	global_store_dwordx4 v[118:119], v[94:97], off sc1 nt
	v_add_f32_e32 v77, v94, v95
	v_add_f32_e32 v81, v96, v97
	global_store_dwordx4 v[118:119], v[90:93], off offset:1024 sc1 nt
	v_mov_b32_e32 v76, v90
	v_mov_b32_e32 v80, v91
	v_pk_add_f32 v[72:73], v[72:73], v[72:73] op_sel_hi:[0,1]
	v_pk_add_f32 v[76:77], v[76:77], v[80:81]
	ds_read_b128 v[80:83], v241 offset:26624
	ds_read_b128 v[208:211], v241 offset:10240
	v_mov_b32_e32 v72, v92
	v_mov_b32_e32 v68, v93
	v_pk_add_f32 v[68:69], v[72:73], v[68:69]
	v_pk_mul_f32 v[72:73], v[86:87], v[102:103] op_sel_hi:[1,0]
	v_pk_add_f32 v[68:69], v[76:77], v[68:69]
	v_pk_mul_f32 v[76:77], v[108:109], v[102:103] op_sel_hi:[1,0]
	ds_read_b128 v[106:109], v241 offset:27648
	ds_read_b128 v[212:215], v241 offset:11264
	s_waitcnt lgkmcnt(2)
	v_pk_fma_f32 v[88:89], v[76:77], v[210:211], v[82:83]
	v_pk_fma_f32 v[86:87], v[72:73], v[208:209], v[80:81]
	v_mov_b32_e32 v77, v89
	v_pk_mov_b32 v[72:73], v[86:87], v[88:89] op_sel:[1,0]
	v_mov_b32_e32 v76, v86
	v_pk_add_f32 v[72:73], v[72:73], v[76:77]
	v_pk_mul_f32 v[76:77], v[84:85], v[102:103] op_sel_hi:[1,0]
	v_pk_mul_f32 v[80:81], v[104:105], v[102:103] op_sel_hi:[1,0]
	s_waitcnt lgkmcnt(0)
	v_pk_fma_f32 v[82:83], v[76:77], v[212:213], v[106:107]
	v_pk_fma_f32 v[84:85], v[80:81], v[214:215], v[108:109]
	global_store_dwordx4 v[118:119], v[86:89], off offset:2048 sc1 nt
	global_store_dwordx4 v[118:119], v[82:85], off offset:3072 sc1 nt
	ds_read_b128 v[104:107], v241 offset:12288
	ds_read_b128 v[108:111], v241 offset:28672
	v_pk_mul_f32 v[118:119], v[122:123], v[102:103] op_sel_hi:[1,0]
	v_pk_mul_f32 v[78:79], v[78:79], v[102:103] op_sel_hi:[1,0]
	v_pk_add_f32 v[68:69], v[68:69], v[68:69] op_sel_hi:[0,1]
	v_pk_add_f32 v[72:73], v[72:73], v[72:73] op_sel_hi:[0,1]
	ds_read_b128 v[122:125], v241 offset:29696
	ds_read_b128 v[208:211], v241 offset:13312
	s_waitcnt lgkmcnt(2)
	v_pk_fma_f32 v[80:81], v[78:79], v[106:107], v[110:111]
	v_pk_fma_f32 v[78:79], v[118:119], v[104:105], v[108:109]
	v_add_f32_e32 v77, v82, v83
	v_add_f32_e32 v101, v84, v85
	v_mov_b32_e32 v76, v78
	v_mov_b32_e32 v100, v79
	v_mov_b32_e32 v72, v80
	v_mov_b32_e32 v68, v81
	v_pk_add_f32 v[76:77], v[76:77], v[100:101]
	v_pk_add_f32 v[68:69], v[72:73], v[68:69]
	v_pk_mul_f32 v[72:73], v[116:117], v[102:103] op_sel_hi:[1,0]
	v_pk_add_f32 v[68:69], v[76:77], v[68:69]
	s_waitcnt lgkmcnt(0)
	v_pk_fma_f32 v[76:77], v[72:73], v[210:211], v[124:125]
	v_pk_add_f32 v[100:101], v[68:69], v[68:69] op_sel:[0,1] op_sel_hi:[1,0]
	v_pk_mul_f32 v[68:69], v[74:75], v[102:103] op_sel_hi:[1,0]
	v_mov_b32_e32 v73, v77
	v_pk_fma_f32 v[74:75], v[68:69], v[208:209], v[122:123]
	ds_read_b128 v[104:107], v241 offset:30720
	ds_read_b128 v[108:111], v241 offset:14336
	v_pk_mov_b32 v[68:69], v[74:75], v[76:77] op_sel:[1,0]
	v_mov_b32_e32 v72, v74
	v_pk_add_f32 v[68:69], v[68:69], v[72:73]
	v_pk_mul_f32 v[66:67], v[66:67], v[102:103] op_sel_hi:[1,0]
	v_pk_add_f32 v[124:125], v[68:69], v[68:69] op_sel:[0,1] op_sel_hi:[1,0]
	v_pk_mul_f32 v[68:69], v[70:71], v[102:103] op_sel_hi:[1,0]
	v_pk_mul_f32 v[70:71], v[120:121], v[102:103] op_sel_hi:[1,0]
	ds_read_b128 v[116:119], v241 offset:31744
	ds_read_b128 v[120:123], v241 offset:15360
	s_waitcnt lgkmcnt(2)
	v_pk_fma_f32 v[72:73], v[70:71], v[110:111], v[106:107]
	v_pk_fma_f32 v[70:71], v[68:69], v[108:109], v[104:105]
	v_pk_mul_f32 v[108:109], v[126:127], v[102:103] op_sel_hi:[1,0]
	v_add_f32_e32 v104, v70, v71
	s_waitcnt lgkmcnt(0)
	v_pk_fma_f32 v[68:69], v[66:67], v[122:123], v[118:119]
	v_pk_fma_f32 v[66:67], v[108:109], v[120:121], v[116:117]
	v_add_f32_e32 v106, v72, v73
	v_mov_b32_e32 v125, v66
	v_mov_b32_e32 v101, v67
	v_mov_b32_e32 v105, v68
	v_mov_b32_e32 v107, v69
	v_pk_add_f32 v[100:101], v[124:125], v[100:101]
	v_pk_add_f32 v[102:103], v[104:105], v[106:107]
	v_add_co_u32_e32 v98, vcc, s78, v98
	v_pk_add_f32 v[100:101], v[100:101], v[102:103]
	s_nop 0
	v_addc_co_u32_e32 v99, vcc, 0, v99, vcc
	v_add_f32_e32 v100, v100, v101
	ds_bpermute_b32 v101, v202, v100
	global_store_dwordx4 v[98:99], v[78:81], off sc1 nt
	global_store_dwordx4 v[98:99], v[74:77], off offset:1024 sc1 nt
	global_store_dwordx4 v[98:99], v[70:73], off offset:2048 sc1 nt
	global_store_dwordx4 v[98:99], v[66:69], off offset:3072 sc1 nt
	s_waitcnt lgkmcnt(0)
	v_add_f32_e32 v100, v100, v101
	ds_bpermute_b32 v101, v203, v100
	s_waitcnt lgkmcnt(0)
	v_add_f32_e32 v100, v100, v101
	ds_bpermute_b32 v101, v204, v100
	s_waitcnt lgkmcnt(0)
	v_add_f32_e32 v100, v100, v101
	ds_bpermute_b32 v101, v205, v100
	s_waitcnt lgkmcnt(0)
	v_add_f32_e32 v100, v100, v101
	ds_bpermute_b32 v101, v206, v100
	s_waitcnt lgkmcnt(0)
	v_add_f32_e32 v100, v100, v101
	ds_bpermute_b32 v101, v207, v100
	s_waitcnt lgkmcnt(0)
	v_add_f32_e32 v106, v100, v101
	v_fmamk_f32 v153, v106, 0xb9800000, v153
	v_fmac_f32_e32 v152, 0xb9800000, v106
	v_fmamk_f32 v155, v106, 0xb9800000, v155
	v_fmac_f32_e32 v154, 0xb9800000, v106
	v_pk_mul_f32 v[98:99], v[154:155], v[154:155]
	v_pk_mul_f32 v[100:101], v[152:153], v[152:153]
	v_fmamk_f32 v149, v106, 0xb9800000, v149
	v_pk_mov_b32 v[102:103], v[100:101], v[98:99] op_sel:[1,0]
	v_mov_b32_e32 v101, v99
	v_pk_add_f32 v[98:99], v[102:103], v[100:101]
	v_fmac_f32_e32 v148, 0xb9800000, v106
	v_fmamk_f32 v151, v106, 0xb9800000, v151
	v_fmac_f32_e32 v150, 0xb9800000, v106
	v_pk_add_f32 v[98:99], v[98:99], v[98:99] op_sel_hi:[0,1]
	v_pk_mul_f32 v[100:101], v[150:151], v[150:151]
	v_pk_mul_f32 v[102:103], v[148:149], v[148:149]
	v_fmac_f32_e32 v144, 0xb9800000, v106
	v_pk_mov_b32 v[104:105], v[102:103], v[100:101] op_sel:[1,0]
	v_mov_b32_e32 v103, v101
	v_fmamk_f32 v145, v106, 0xb9800000, v145
	v_fmac_f32_e32 v146, 0xb9800000, v106
	v_mul_f32_e32 v98, v144, v144
	v_pk_add_f32 v[100:101], v[104:105], v[102:103]
	v_fmamk_f32 v147, v106, 0xb9800000, v147
	v_pk_fma_f32 v[102:103], v[144:145], v[144:145], v[98:99] op_sel_hi:[1,1,0]
	v_mul_f32_e32 v98, v146, v146
	v_pk_add_f32 v[100:101], v[100:101], v[100:101] op_sel_hi:[0,1]
	v_pk_fma_f32 v[104:105], v[146:147], v[146:147], v[98:99] op_sel_hi:[1,1,0]
	v_fmamk_f32 v143, v106, 0xb9800000, v143
	v_fmac_f32_e32 v142, 0xb9800000, v106
	v_fmamk_f32 v141, v106, 0xb9800000, v141
	v_fmac_f32_e32 v140, 0xb9800000, v106
	v_mul_f32_e32 v102, v140, v140
	v_mul_f32_e32 v104, v141, v141
	v_mul_f32_e32 v98, v142, v142
	v_mul_f32_e32 v100, v143, v143
	v_pk_add_f32 v[102:103], v[102:103], v[104:105]
	v_pk_add_f32 v[98:99], v[98:99], v[100:101]
	v_fmamk_f32 v137, v106, 0xb9800000, v137
	v_pk_add_f32 v[98:99], v[102:103], v[98:99]
	v_fmac_f32_e32 v136, 0xb9800000, v106
	v_fmamk_f32 v139, v106, 0xb9800000, v139
	v_fmac_f32_e32 v138, 0xb9800000, v106
	v_pk_add_f32 v[98:99], v[98:99], v[98:99] op_sel_hi:[0,1]
	v_pk_mul_f32 v[100:101], v[138:139], v[138:139]
	v_pk_mul_f32 v[102:103], v[136:137], v[136:137]
	v_fmac_f32_e32 v132, 0xb9800000, v106
	v_pk_mov_b32 v[104:105], v[102:103], v[100:101] op_sel:[1,0]
	v_mov_b32_e32 v103, v101
	v_fmamk_f32 v133, v106, 0xb9800000, v133
	v_fmac_f32_e32 v134, 0xb9800000, v106
	v_mul_f32_e32 v98, v132, v132
	v_pk_add_f32 v[100:101], v[104:105], v[102:103]
	v_fmamk_f32 v135, v106, 0xb9800000, v135
	v_pk_fma_f32 v[102:103], v[132:133], v[132:133], v[98:99] op_sel_hi:[1,1,0]
	v_mul_f32_e32 v98, v134, v134
	v_pk_add_f32 v[100:101], v[100:101], v[100:101] op_sel_hi:[0,1]
	v_pk_fma_f32 v[104:105], v[134:135], v[134:135], v[98:99] op_sel_hi:[1,1,0]
	v_fmamk_f32 v131, v106, 0xb9800000, v131
	v_fmac_f32_e32 v130, 0xb9800000, v106
	v_fmamk_f32 v129, v106, 0xb9800000, v129
	v_fmac_f32_e32 v128, 0xb9800000, v106
	v_mul_f32_e32 v102, v128, v128
	v_mul_f32_e32 v104, v129, v129
	v_mul_f32_e32 v100, v130, v130
	v_mul_f32_e32 v98, v131, v131
	v_pk_add_f32 v[102:103], v[102:103], v[104:105]
	v_pk_add_f32 v[98:99], v[100:101], v[98:99]
	v_fmamk_f32 v113, v106, 0xb9800000, v113
	v_pk_add_f32 v[98:99], v[102:103], v[98:99]
	v_fmac_f32_e32 v112, 0xb9800000, v106
	v_fmamk_f32 v115, v106, 0xb9800000, v115
	v_fmac_f32_e32 v114, 0xb9800000, v106
	v_pk_add_f32 v[98:99], v[98:99], v[98:99] op_sel_hi:[0,1]
	v_pk_mul_f32 v[100:101], v[114:115], v[114:115]
	v_pk_mul_f32 v[102:103], v[112:113], v[112:113]
	v_fmac_f32_e32 v94, 0xb9800000, v106
	v_pk_mov_b32 v[104:105], v[102:103], v[100:101] op_sel:[1,0]
	v_mov_b32_e32 v103, v101
	v_fmamk_f32 v95, v106, 0xb9800000, v95
	v_fmac_f32_e32 v96, 0xb9800000, v106
	v_mul_f32_e32 v98, v94, v94
	v_pk_add_f32 v[100:101], v[104:105], v[102:103]
	v_fmamk_f32 v97, v106, 0xb9800000, v97
	v_pk_fma_f32 v[102:103], v[94:95], v[94:95], v[98:99] op_sel_hi:[1,1,0]
	v_mul_f32_e32 v98, v96, v96
	v_pk_add_f32 v[100:101], v[100:101], v[100:101] op_sel_hi:[0,1]
	v_pk_fma_f32 v[104:105], v[96:97], v[96:97], v[98:99] op_sel_hi:[1,1,0]
	v_fmamk_f32 v93, v106, 0xb9800000, v93
	v_fmac_f32_e32 v92, 0xb9800000, v106
	v_fmamk_f32 v91, v106, 0xb9800000, v91
	v_fmac_f32_e32 v90, 0xb9800000, v106
	v_mul_f32_e32 v102, v90, v90
	v_mul_f32_e32 v104, v91, v91
	v_mul_f32_e32 v100, v92, v92
	v_mul_f32_e32 v98, v93, v93
	v_pk_add_f32 v[102:103], v[102:103], v[104:105]
	v_pk_add_f32 v[98:99], v[100:101], v[98:99]
	v_fmamk_f32 v87, v106, 0xb9800000, v87
	v_pk_add_f32 v[98:99], v[102:103], v[98:99]
	v_fmac_f32_e32 v86, 0xb9800000, v106
	v_fmamk_f32 v89, v106, 0xb9800000, v89
	v_fmac_f32_e32 v88, 0xb9800000, v106
	v_pk_add_f32 v[98:99], v[98:99], v[98:99] op_sel_hi:[0,1]
	v_pk_mul_f32 v[100:101], v[88:89], v[88:89]
	v_pk_mul_f32 v[102:103], v[86:87], v[86:87]
	v_fmac_f32_e32 v82, 0xb9800000, v106
	v_pk_mov_b32 v[104:105], v[102:103], v[100:101] op_sel:[1,0]
	v_mov_b32_e32 v103, v101
	v_fmamk_f32 v83, v106, 0xb9800000, v83
	v_fmac_f32_e32 v84, 0xb9800000, v106
	v_mul_f32_e32 v98, v82, v82
	v_pk_add_f32 v[100:101], v[104:105], v[102:103]
	v_fmamk_f32 v85, v106, 0xb9800000, v85
	v_pk_fma_f32 v[102:103], v[82:83], v[82:83], v[98:99] op_sel_hi:[1,1,0]
	v_mul_f32_e32 v98, v84, v84
	v_pk_add_f32 v[100:101], v[100:101], v[100:101] op_sel_hi:[0,1]
	v_pk_fma_f32 v[104:105], v[84:85], v[84:85], v[98:99] op_sel_hi:[1,1,0]
	v_fmamk_f32 v81, v106, 0xb9800000, v81
	v_fmac_f32_e32 v80, 0xb9800000, v106
	v_fmamk_f32 v79, v106, 0xb9800000, v79
	v_fmac_f32_e32 v78, 0xb9800000, v106
	v_mul_f32_e32 v102, v78, v78
	v_mul_f32_e32 v104, v79, v79
	v_mul_f32_e32 v100, v80, v80
	v_mul_f32_e32 v98, v81, v81
	v_pk_add_f32 v[102:103], v[102:103], v[104:105]
	v_pk_add_f32 v[98:99], v[100:101], v[98:99]
	v_fmamk_f32 v75, v106, 0xb9800000, v75
	v_pk_add_f32 v[98:99], v[102:103], v[98:99]
	v_fmac_f32_e32 v74, 0xb9800000, v106
	v_fmamk_f32 v77, v106, 0xb9800000, v77
	v_fmac_f32_e32 v76, 0xb9800000, v106
	v_pk_add_f32 v[98:99], v[98:99], v[98:99] op_sel_hi:[0,1]
	v_pk_mul_f32 v[100:101], v[76:77], v[76:77]
	v_pk_mul_f32 v[102:103], v[74:75], v[74:75]
	v_fmac_f32_e32 v70, 0xb9800000, v106
	v_pk_mov_b32 v[104:105], v[102:103], v[100:101] op_sel:[1,0]
	v_mov_b32_e32 v103, v101
	v_fmamk_f32 v71, v106, 0xb9800000, v71
	v_fmac_f32_e32 v72, 0xb9800000, v106
	v_mul_f32_e32 v98, v70, v70
	v_pk_add_f32 v[100:101], v[104:105], v[102:103]
	v_fmamk_f32 v73, v106, 0xb9800000, v73
	v_pk_fma_f32 v[102:103], v[70:71], v[70:71], v[98:99] op_sel_hi:[1,1,0]
	v_mul_f32_e32 v98, v72, v72
	v_pk_add_f32 v[100:101], v[100:101], v[100:101] op_sel_hi:[0,1]
	v_pk_fma_f32 v[104:105], v[72:73], v[72:73], v[98:99] op_sel_hi:[1,1,0]
	v_fmamk_f32 v69, v106, 0xb9800000, v69
	v_fmac_f32_e32 v68, 0xb9800000, v106
	v_fmamk_f32 v67, v106, 0xb9800000, v67
	v_fmac_f32_e32 v66, 0xb9800000, v106
	v_mul_f32_e32 v102, v66, v66
	v_mul_f32_e32 v104, v67, v67
	v_mul_f32_e32 v100, v68, v68
	v_mul_f32_e32 v98, v69, v69
	v_pk_add_f32 v[102:103], v[102:103], v[104:105]
	v_pk_add_f32 v[98:99], v[100:101], v[98:99]
	s_nop 0
	v_pk_add_f32 v[98:99], v[102:103], v[98:99]
	s_nop 0
	v_add_f32_e32 v98, v98, v99
	ds_bpermute_b32 v99, v202, v98
	s_waitcnt lgkmcnt(0)
	v_add_f32_e32 v98, v98, v99
	ds_bpermute_b32 v99, v203, v98
	s_waitcnt lgkmcnt(0)
	v_add_f32_e32 v98, v98, v99
	ds_bpermute_b32 v99, v204, v98
	s_waitcnt lgkmcnt(0)
	v_add_f32_e32 v98, v98, v99
	ds_bpermute_b32 v99, v205, v98
	s_waitcnt lgkmcnt(0)
	v_add_f32_e32 v98, v98, v99
	ds_bpermute_b32 v99, v206, v98
	s_waitcnt lgkmcnt(0)
	v_add_f32_e32 v98, v98, v99
	ds_bpermute_b32 v99, v207, v98
	s_waitcnt lgkmcnt(0)
	v_add_f32_e32 v98, v98, v99
	v_fmamk_f32 v98, v98, 0x39800000, v179
	v_mul_f32_e32 v99, 0x4f800000, v98
	v_cmp_gt_f32_e32 vcc, s79, v98
	s_nop 1
	v_cndmask_b32_e32 v98, v98, v99, vcc
	v_sqrt_f32_e32 v99, v98
	s_nop 0
	v_add_u32_e32 v100, -1, v99
	v_fma_f32 v101, -v100, v99, v98
	v_cmp_ge_f32_e64 s[0:1], 0, v101
	v_add_u32_e32 v101, 1, v99
	s_nop 0
	v_cndmask_b32_e64 v100, v99, v100, s[0:1]
	v_fma_f32 v99, -v101, v99, v98
	v_cmp_lt_f32_e64 s[0:1], 0, v99
	s_nop 1
	v_cndmask_b32_e64 v99, v100, v101, s[0:1]
	v_mul_f32_e32 v100, 0x37800000, v99
	v_cndmask_b32_e32 v99, v99, v100, vcc
	v_cmp_class_f32_e32 vcc, v98, v242
	s_nop 1
	v_cndmask_b32_e32 v98, v99, v98, vcc
	v_div_scale_f32 v99, s[0:1], v98, v98, 1.0
	v_rcp_f32_e32 v100, v99
	s_lshl_b64 s[0:1], s[46:47], 12
	s_and_b64 s[8:9], s[48:49], exec
	s_cselect_b32 s2, 0, s2
	v_fma_f32 v101, -v99, v100, 1.0
	v_fmac_f32_e32 v100, v101, v100
	v_div_scale_f32 v101, vcc, 1.0, v98, 1.0
	v_mul_f32_e32 v102, v101, v100
	v_fma_f32 v103, -v99, v102, v101
	v_fmac_f32_e32 v102, v103, v100
	v_fma_f32 v99, -v99, v102, v101
	v_div_fmas_f32 v104, v99, v100, v102
	v_add_u32_e32 v99, s2, v241
	ds_read_b128 v[100:103], v99 offset:49152
	ds_read_b128 v[108:111], v99 offset:50176
	v_div_fixup_f32 v98, v104, v98, 1.0
	ds_read_b128 v[104:107], v99 offset:32768
	ds_read_b128 v[116:119], v99 offset:33792
	v_pk_mul_f32 v[120:121], v[152:153], v[98:99] op_sel_hi:[1,0]
	s_waitcnt lgkmcnt(3)
	v_pk_add_f32 v[100:101], v[100:101], 1.0 op_sel_hi:[1,0]
	v_pk_add_f32 v[102:103], v[102:103], 1.0 op_sel_hi:[1,0]
	s_waitcnt lgkmcnt(1)
	v_pk_fma_f32 v[104:105], v[100:101], v[120:121], v[104:105]
	v_mov_b32_e32 v120, v193
	v_cvt_pk_fp8_f32 v120, v104, v105
	v_pk_mul_f32 v[100:101], v[154:155], v[98:99] op_sel_hi:[1,0]
	v_pk_add_f32 v[108:109], v[108:109], 1.0 op_sel_hi:[1,0]
	v_pk_fma_f32 v[106:107], v[102:103], v[100:101], v[106:107]
	v_lshl_add_u64 v[100:101], v[198:199], 0, s[0:1]
	v_cvt_pk_fp8_f32 v120, v106, v107 op_sel:[0,0,1]
	v_pk_add_f32 v[110:111], v[110:111], 1.0 op_sel_hi:[1,0]
	s_lshl_b64 s[0:1], s[46:47], 13
	v_lshl_add_u64 v[102:103], v[194:195], 0, s[0:1]
	global_store_dword v[100:101], v120, off sc1
	v_bfe_u32 v120, v104, 16, 1
	v_add3_u32 v104, v104, v120, s80
	v_bfe_u32 v120, v105, 16, 1
	v_add3_u32 v105, v105, v120, s80
	v_pk_mul_f32 v[120:121], v[148:149], v[98:99] op_sel_hi:[1,0]
	v_lshrrev_b32_e32 v104, 16, v104
	s_waitcnt lgkmcnt(0)
	v_pk_fma_f32 v[108:109], v[108:109], v[120:121], v[116:117]
	v_mov_b32_e32 v120, v193
	v_cvt_pk_fp8_f32 v120, v108, v109
	v_pk_mul_f32 v[116:117], v[150:151], v[98:99] op_sel_hi:[1,0]
	v_and_or_b32 v104, v105, s76, v104
	v_bfe_u32 v105, v106, 16, 1
	v_pk_fma_f32 v[124:125], v[110:111], v[116:117], v[118:119]
	v_add3_u32 v105, v106, v105, s80
	v_bfe_u32 v106, v107, 16, 1
	v_cvt_pk_fp8_f32 v120, v124, v125 op_sel:[0,0,1]
	v_lshrrev_b32_e32 v105, 16, v105
	v_add3_u32 v106, v107, v106, s80
	v_and_or_b32 v105, v106, s76, v105
	global_store_dwordx2 v[102:103], v[104:105], off sc1
	global_store_dword v[100:101], v120, off offset:256 sc1
	v_bfe_u32 v104, v108, 16, 1
	v_add3_u32 v104, v108, v104, s80
	v_bfe_u32 v105, v109, 16, 1
	v_lshrrev_b32_e32 v104, 16, v104
	v_add3_u32 v105, v109, v105, s80
	v_and_or_b32 v126, v105, s76, v104
	v_bfe_u32 v104, v124, 16, 1
	v_add3_u32 v104, v124, v104, s80
	v_lshrrev_b32_e32 v124, 16, v104
	ds_read_b128 v[104:107], v99 offset:51200
	ds_read_b128 v[116:119], v99 offset:52224
	ds_read_b128 v[108:111], v99 offset:34816
	ds_read_b128 v[120:123], v99 offset:35840
	v_pk_mul_f32 v[144:145], v[144:145], v[98:99] op_sel_hi:[1,0]
	s_waitcnt lgkmcnt(3)
	v_pk_add_f32 v[104:105], v[104:105], 1.0 op_sel_hi:[1,0]
	v_bfe_u32 v127, v125, 16, 1
	s_waitcnt lgkmcnt(1)
	v_pk_fma_f32 v[104:105], v[104:105], v[144:145], v[108:109]
	v_pk_mul_f32 v[108:109], v[146:147], v[98:99] op_sel_hi:[1,0]
	v_pk_add_f32 v[106:107], v[106:107], 1.0 op_sel_hi:[1,0]
	v_mov_b32_e32 v144, v193
	v_pk_fma_f32 v[106:107], v[106:107], v[108:109], v[110:111]
	v_add3_u32 v108, v125, v127, s80
	v_and_or_b32 v127, v108, s76, v124
	v_bfe_u32 v108, v104, 16, 1
	v_cvt_pk_fp8_f32 v144, v104, v105
	v_add3_u32 v104, v104, v108, s80
	v_bfe_u32 v108, v105, 16, 1
	v_add3_u32 v105, v105, v108, s80
	v_pk_mul_f32 v[108:109], v[140:141], v[98:99] op_sel_hi:[1,0]
	v_pk_add_f32 v[110:111], v[116:117], 1.0 op_sel_hi:[1,0]
	v_lshrrev_b32_e32 v104, 16, v104
	s_waitcnt lgkmcnt(0)
	v_pk_fma_f32 v[108:109], v[110:111], v[108:109], v[120:121]
	v_mov_b32_e32 v120, v193
	v_cvt_pk_fp8_f32 v120, v108, v109
	v_pk_mul_f32 v[110:111], v[142:143], v[98:99] op_sel_hi:[1,0]
	v_pk_add_f32 v[116:117], v[118:119], 1.0 op_sel_hi:[1,0]
	v_and_or_b32 v104, v105, s76, v104
	v_bfe_u32 v105, v106, 16, 1
	v_pk_fma_f32 v[110:111], v[116:117], v[110:111], v[122:123]
	v_cvt_pk_fp8_f32 v144, v106, v107 op_sel:[0,0,1]
	v_add3_u32 v105, v106, v105, s80
	v_bfe_u32 v106, v107, 16, 1
	v_cvt_pk_fp8_f32 v120, v110, v111 op_sel:[0,0,1]
	v_lshrrev_b32_e32 v105, 16, v105
	v_add3_u32 v106, v107, v106, s80
	v_and_or_b32 v105, v106, s76, v105
	global_store_dwordx2 v[102:103], v[126:127], off offset:512 sc1
	global_store_dword v[100:101], v144, off offset:512 sc1
	global_store_dwordx2 v[102:103], v[104:105], off offset:1024 sc1
	global_store_dword v[100:101], v120, off offset:768 sc1
	v_bfe_u32 v104, v108, 16, 1
	v_add3_u32 v104, v108, v104, s80
	v_bfe_u32 v105, v109, 16, 1
	v_lshrrev_b32_e32 v104, 16, v104
	v_add3_u32 v105, v109, v105, s80
	v_and_or_b32 v104, v105, s76, v104
	v_bfe_u32 v105, v110, 16, 1
	v_add3_u32 v105, v110, v105, s80
	v_bfe_u32 v106, v111, 16, 1
	v_lshrrev_b32_e32 v105, 16, v105
	v_add3_u32 v106, v111, v106, s80
	v_and_or_b32 v105, v106, s76, v105
	global_store_dwordx2 v[102:103], v[104:105], off offset:1536 sc1
	ds_read_b128 v[104:107], v99 offset:53248
	ds_read_b128 v[108:111], v99 offset:36864
	v_pk_mul_f32 v[124:125], v[136:137], v[98:99] op_sel_hi:[1,0]
	ds_read_b128 v[116:119], v99 offset:54272
	ds_read_b128 v[120:123], v99 offset:37888
	s_waitcnt lgkmcnt(3)
	v_pk_add_f32 v[104:105], v[104:105], 1.0 op_sel_hi:[1,0]
	v_pk_add_f32 v[106:107], v[106:107], 1.0 op_sel_hi:[1,0]
	s_waitcnt lgkmcnt(2)
	v_pk_fma_f32 v[104:105], v[104:105], v[124:125], v[108:109]
	v_mov_b32_e32 v124, v193
	v_cvt_pk_fp8_f32 v124, v104, v105
	v_pk_mul_f32 v[108:109], v[138:139], v[98:99] op_sel_hi:[1,0]
	v_pk_mul_f32 v[128:129], v[128:129], v[98:99] op_sel_hi:[1,0]
	v_pk_fma_f32 v[106:107], v[106:107], v[108:109], v[110:111]
	v_bfe_u32 v108, v104, 16, 1
	v_add3_u32 v104, v104, v108, s80
	v_bfe_u32 v108, v105, 16, 1
	v_add3_u32 v105, v105, v108, s80
	v_pk_mul_f32 v[108:109], v[132:133], v[98:99] op_sel_hi:[1,0]
	s_waitcnt lgkmcnt(1)
	v_pk_add_f32 v[110:111], v[116:117], 1.0 op_sel_hi:[1,0]
	v_cvt_pk_fp8_f32 v124, v106, v107 op_sel:[0,0,1]
	s_waitcnt lgkmcnt(0)
	v_pk_fma_f32 v[108:109], v[108:109], v[110:111], v[120:121]
	v_mov_b32_e32 v120, v193
	v_cvt_pk_fp8_f32 v120, v108, v109
	v_lshrrev_b32_e32 v104, 16, v104
	v_pk_mul_f32 v[110:111], v[134:135], v[98:99] op_sel_hi:[1,0]
	v_pk_add_f32 v[116:117], v[118:119], 1.0 op_sel_hi:[1,0]
	global_store_dword v[100:101], v124, off offset:1024 sc1
	v_and_or_b32 v104, v105, s76, v104
	v_bfe_u32 v105, v106, 16, 1
	v_pk_fma_f32 v[124:125], v[110:111], v[116:117], v[122:123]
	v_add3_u32 v105, v106, v105, s80
	v_bfe_u32 v106, v107, 16, 1
	v_cvt_pk_fp8_f32 v120, v124, v125 op_sel:[0,0,1]
	v_lshrrev_b32_e32 v105, 16, v105
	v_add3_u32 v106, v107, v106, s80
	v_and_or_b32 v105, v106, s76, v105
	global_store_dwordx2 v[102:103], v[104:105], off offset:2048 sc1
	global_store_dword v[100:101], v120, off offset:1280 sc1
	v_bfe_u32 v104, v108, 16, 1
	v_add3_u32 v104, v108, v104, s80
	v_bfe_u32 v105, v109, 16, 1
	v_lshrrev_b32_e32 v104, 16, v104
	v_add3_u32 v105, v109, v105, s80
	v_and_or_b32 v126, v105, s76, v104
	v_bfe_u32 v104, v124, 16, 1
	v_add3_u32 v104, v124, v104, s80
	v_lshrrev_b32_e32 v124, 16, v104
	ds_read_b128 v[104:107], v99 offset:55296
	ds_read_b128 v[116:119], v99 offset:56320
	ds_read_b128 v[108:111], v99 offset:38912
	ds_read_b128 v[120:123], v99 offset:39936
	v_bfe_u32 v127, v125, 16, 1
	s_waitcnt lgkmcnt(3)
	v_pk_add_f32 v[104:105], v[104:105], 1.0 op_sel_hi:[1,0]
	v_pk_add_f32 v[106:107], v[106:107], 1.0 op_sel_hi:[1,0]
	s_waitcnt lgkmcnt(1)
	v_pk_fma_f32 v[104:105], v[128:129], v[104:105], v[108:109]
	v_pk_mul_f32 v[108:109], v[130:131], v[98:99] op_sel_hi:[1,0]
	v_mov_b32_e32 v128, v193
	v_pk_fma_f32 v[106:107], v[108:109], v[106:107], v[110:111]
	v_add3_u32 v108, v125, v127, s80
	v_and_or_b32 v127, v108, s76, v124
	v_bfe_u32 v108, v104, 16, 1
	v_cvt_pk_fp8_f32 v128, v104, v105
	v_add3_u32 v104, v104, v108, s80
	v_bfe_u32 v108, v105, 16, 1
	v_add3_u32 v105, v105, v108, s80
	v_pk_mul_f32 v[108:109], v[112:113], v[98:99] op_sel_hi:[1,0]
	v_pk_add_f32 v[110:111], v[116:117], 1.0 op_sel_hi:[1,0]
	v_mov_b32_e32 v116, v193
	s_waitcnt lgkmcnt(0)
	v_pk_fma_f32 v[108:109], v[108:109], v[110:111], v[120:121]
	v_lshrrev_b32_e32 v104, 16, v104
	v_cvt_pk_fp8_f32 v116, v108, v109
	v_pk_mul_f32 v[110:111], v[114:115], v[98:99] op_sel_hi:[1,0]
	v_pk_add_f32 v[112:113], v[118:119], 1.0 op_sel_hi:[1,0]
	v_and_or_b32 v104, v105, s76, v104
	v_bfe_u32 v105, v106, 16, 1
	v_pk_fma_f32 v[110:111], v[110:111], v[112:113], v[122:123]
	v_cvt_pk_fp8_f32 v128, v106, v107 op_sel:[0,0,1]
	v_add3_u32 v105, v106, v105, s80
	v_bfe_u32 v106, v107, 16, 1
	v_cvt_pk_fp8_f32 v116, v110, v111 op_sel:[0,0,1]
	v_lshrrev_b32_e32 v105, 16, v105
	v_add3_u32 v106, v107, v106, s80
	v_and_or_b32 v105, v106, s76, v105
	global_store_dwordx2 v[102:103], v[126:127], off offset:2560 sc1
	global_store_dword v[100:101], v128, off offset:1536 sc1
	global_store_dwordx2 v[102:103], v[104:105], off offset:3072 sc1
	global_store_dword v[100:101], v116, off offset:1792 sc1
	v_bfe_u32 v104, v108, 16, 1
	v_add3_u32 v104, v108, v104, s80
	v_bfe_u32 v105, v109, 16, 1
	v_lshrrev_b32_e32 v104, 16, v104
	v_add3_u32 v105, v109, v105, s80
	v_and_or_b32 v104, v105, s76, v104
	v_bfe_u32 v105, v110, 16, 1
	v_add3_u32 v105, v110, v105, s80
	v_bfe_u32 v106, v111, 16, 1
	v_lshrrev_b32_e32 v105, 16, v105
	v_add3_u32 v106, v111, v106, s80
	v_and_or_b32 v105, v106, s76, v105
	global_store_dwordx2 v[102:103], v[104:105], off offset:3584 sc1
	ds_read_b128 v[104:107], v99 offset:57344
	ds_read_b128 v[108:111], v99 offset:40960
	v_pk_mul_f32 v[94:95], v[94:95], v[98:99] op_sel_hi:[1,0]
	v_pk_mul_f32 v[96:97], v[96:97], v[98:99] op_sel_hi:[1,0]
	ds_read_b128 v[112:115], v99 offset:58368
	ds_read_b128 v[116:119], v99 offset:41984
	s_waitcnt lgkmcnt(3)
	v_pk_add_f32 v[104:105], v[104:105], 1.0 op_sel_hi:[1,0]
	v_pk_mul_f32 v[90:91], v[90:91], v[98:99] op_sel_hi:[1,0]
	s_waitcnt lgkmcnt(2)
	v_pk_fma_f32 v[94:95], v[94:95], v[104:105], v[108:109]
	v_mov_b32_e32 v108, v193
	v_pk_add_f32 v[104:105], v[106:107], 1.0 op_sel_hi:[1,0]
	v_cvt_pk_fp8_f32 v108, v94, v95
	v_pk_fma_f32 v[96:97], v[96:97], v[104:105], v[110:111]
	v_bfe_u32 v104, v94, 16, 1
	v_add3_u32 v94, v94, v104, s80
	v_bfe_u32 v104, v95, 16, 1
	v_lshrrev_b32_e32 v94, 16, v94
	v_add3_u32 v95, v95, v104, s80
	v_and_or_b32 v94, v95, s76, v94
	v_bfe_u32 v95, v96, 16, 1
	v_cvt_pk_fp8_f32 v108, v96, v97 op_sel:[0,0,1]
	v_add3_u32 v95, v96, v95, s80
	v_bfe_u32 v96, v97, 16, 1
	v_lshrrev_b32_e32 v95, 16, v95
	v_add3_u32 v96, v97, v96, s80
	v_and_or_b32 v95, v96, s76, v95
	s_waitcnt lgkmcnt(1)
	v_pk_add_f32 v[96:97], v[112:113], 1.0 op_sel_hi:[1,0]
	v_mov_b32_e32 v104, v193
	s_waitcnt lgkmcnt(0)
	v_pk_fma_f32 v[96:97], v[90:91], v[96:97], v[116:117]
	v_pk_mul_f32 v[90:91], v[92:93], v[98:99] op_sel_hi:[1,0]
	v_cvt_pk_fp8_f32 v104, v96, v97
	v_pk_add_f32 v[92:93], v[114:115], 1.0 op_sel_hi:[1,0]
	global_store_dword v[100:101], v108, off offset:2048 sc1
	v_pk_fma_f32 v[114:115], v[90:91], v[92:93], v[118:119]
	v_bfe_u32 v92, v96, 16, 1
	v_cvt_pk_fp8_f32 v104, v114, v115 op_sel:[0,0,1]
	v_add3_u32 v92, v96, v92, s80
	v_bfe_u32 v93, v97, 16, 1
	v_add_co_u32_e32 v90, vcc, s77, v102
	v_lshrrev_b32_e32 v92, 16, v92
	v_add3_u32 v93, v97, v93, s80
	v_addc_co_u32_e32 v91, vcc, 0, v103, vcc
	v_and_or_b32 v96, v93, s76, v92
	v_bfe_u32 v92, v114, 16, 1
	global_store_dwordx2 v[90:91], v[94:95], off sc1
	global_store_dword v[100:101], v104, off offset:2304 sc1
	v_add3_u32 v92, v114, v92, s80
	v_lshrrev_b32_e32 v97, 16, v92
	ds_read_b128 v[92:95], v99 offset:59392
	ds_read_b128 v[106:109], v99 offset:60416
	ds_read_b128 v[102:105], v99 offset:43008
	ds_read_b128 v[110:113], v99 offset:44032
	v_pk_mul_f32 v[86:87], v[86:87], v[98:99] op_sel_hi:[1,0]
	s_waitcnt lgkmcnt(3)
	v_pk_add_f32 v[92:93], v[92:93], 1.0 op_sel_hi:[1,0]
	v_bfe_u32 v114, v115, 16, 1
	s_waitcnt lgkmcnt(1)
	v_pk_fma_f32 v[86:87], v[86:87], v[92:93], v[102:103]
	v_pk_mul_f32 v[88:89], v[88:89], v[98:99] op_sel_hi:[1,0]
	v_pk_add_f32 v[92:93], v[94:95], 1.0 op_sel_hi:[1,0]
	v_mov_b32_e32 v102, v193
	v_pk_fma_f32 v[88:89], v[88:89], v[92:93], v[104:105]
	v_add3_u32 v92, v115, v114, s80
	v_and_or_b32 v97, v92, s76, v97
	v_bfe_u32 v92, v86, 16, 1
	v_cvt_pk_fp8_f32 v102, v86, v87
	v_add3_u32 v86, v86, v92, s80
	v_bfe_u32 v92, v87, 16, 1
	v_add3_u32 v87, v87, v92, s80
	v_pk_mul_f32 v[82:83], v[82:83], v[98:99] op_sel_hi:[1,0]
	v_pk_add_f32 v[92:93], v[106:107], 1.0 op_sel_hi:[1,0]
	v_mov_b32_e32 v94, v193
	s_waitcnt lgkmcnt(0)
	v_pk_fma_f32 v[82:83], v[82:83], v[92:93], v[110:111]
	v_lshrrev_b32_e32 v86, 16, v86
	v_cvt_pk_fp8_f32 v94, v82, v83
	v_pk_mul_f32 v[84:85], v[84:85], v[98:99] op_sel_hi:[1,0]
	v_pk_add_f32 v[92:93], v[108:109], 1.0 op_sel_hi:[1,0]
	v_and_or_b32 v86, v87, s76, v86
	v_bfe_u32 v87, v88, 16, 1
	v_pk_fma_f32 v[84:85], v[84:85], v[92:93], v[112:113]
	v_cvt_pk_fp8_f32 v102, v88, v89 op_sel:[0,0,1]
	v_add3_u32 v87, v88, v87, s80
	v_bfe_u32 v88, v89, 16, 1
	v_cvt_pk_fp8_f32 v94, v84, v85 op_sel:[0,0,1]
	v_lshrrev_b32_e32 v87, 16, v87
	v_add3_u32 v88, v89, v88, s80
	v_and_or_b32 v87, v88, s76, v87
	global_store_dwordx2 v[90:91], v[96:97], off offset:512 sc1
	global_store_dword v[100:101], v102, off offset:2560 sc1
	global_store_dwordx2 v[90:91], v[86:87], off offset:1024 sc1
	global_store_dword v[100:101], v94, off offset:2816 sc1
	v_bfe_u32 v86, v82, 16, 1
	v_add3_u32 v82, v82, v86, s80
	v_bfe_u32 v86, v83, 16, 1
	v_lshrrev_b32_e32 v82, 16, v82
	v_add3_u32 v83, v83, v86, s80
	v_and_or_b32 v82, v83, s76, v82
	v_bfe_u32 v83, v84, 16, 1
	v_add3_u32 v83, v84, v83, s80
	v_bfe_u32 v84, v85, 16, 1
	v_lshrrev_b32_e32 v83, 16, v83
	v_add3_u32 v84, v85, v84, s80
	v_and_or_b32 v83, v84, s76, v83
	global_store_dwordx2 v[90:91], v[82:83], off offset:1536 sc1
	ds_read_b128 v[82:85], v99 offset:61440
	ds_read_b128 v[86:89], v99 offset:45056
	ds_read_b128 v[92:95], v99 offset:62464
	ds_read_b128 v[102:105], v99 offset:46080
	v_pk_mul_f32 v[78:79], v[78:79], v[98:99] op_sel_hi:[1,0]
	s_waitcnt lgkmcnt(3)
	v_pk_add_f32 v[82:83], v[82:83], 1.0 op_sel_hi:[1,0]
	v_pk_mul_f32 v[80:81], v[80:81], v[98:99] op_sel_hi:[1,0]
	s_waitcnt lgkmcnt(2)
	v_pk_fma_f32 v[78:79], v[78:79], v[82:83], v[86:87]
	v_pk_add_f32 v[82:83], v[84:85], 1.0 op_sel_hi:[1,0]
	v_mov_b32_e32 v86, v193
	v_pk_fma_f32 v[80:81], v[80:81], v[82:83], v[88:89]
	v_bfe_u32 v82, v78, 16, 1
	v_cvt_pk_fp8_f32 v86, v78, v79
	v_add3_u32 v78, v78, v82, s80
	v_bfe_u32 v82, v79, 16, 1
	v_add3_u32 v79, v79, v82, s80
	v_pk_mul_f32 v[74:75], v[74:75], v[98:99] op_sel_hi:[1,0]
	s_waitcnt lgkmcnt(1)
	v_pk_add_f32 v[82:83], v[92:93], 1.0 op_sel_hi:[1,0]
	v_lshrrev_b32_e32 v78, 16, v78
	s_waitcnt lgkmcnt(0)
	v_pk_fma_f32 v[74:75], v[74:75], v[82:83], v[102:103]
	v_mov_b32_e32 v84, v193
	v_and_or_b32 v78, v79, s76, v78
	v_bfe_u32 v79, v80, 16, 1
	v_cvt_pk_fp8_f32 v84, v74, v75
	v_cvt_pk_fp8_f32 v86, v80, v81 op_sel:[0,0,1]
	v_add3_u32 v79, v80, v79, s80
	v_bfe_u32 v80, v81, 16, 1
	v_pk_mul_f32 v[76:77], v[76:77], v[98:99] op_sel_hi:[1,0]
	v_pk_add_f32 v[82:83], v[94:95], 1.0 op_sel_hi:[1,0]
	v_lshrrev_b32_e32 v79, 16, v79
	v_pk_fma_f32 v[92:93], v[76:77], v[82:83], v[104:105]
	v_add3_u32 v76, v81, v80, s80
	v_and_or_b32 v79, v76, s76, v79
	v_bfe_u32 v76, v74, 16, 1
	v_cvt_pk_fp8_f32 v84, v92, v93 op_sel:[0,0,1]
	v_add3_u32 v74, v74, v76, s80
	v_bfe_u32 v76, v75, 16, 1
	v_lshrrev_b32_e32 v74, 16, v74
	v_add3_u32 v75, v75, v76, s80
	v_and_or_b32 v94, v75, s76, v74
	v_bfe_u32 v74, v92, 16, 1
	global_store_dword v[100:101], v86, off offset:3072 sc1
	global_store_dwordx2 v[90:91], v[78:79], off offset:2048 sc1
	global_store_dword v[100:101], v84, off offset:3328 sc1
	v_add3_u32 v74, v92, v74, s80
	v_lshrrev_b32_e32 v92, 16, v74
	ds_read_b128 v[74:77], v99 offset:63488
	ds_read_b128 v[82:85], v99 offset:64512
	ds_read_b128 v[78:81], v99 offset:47104
	ds_read_b128 v[86:89], v99 offset:48128
	v_pk_mul_f32 v[70:71], v[70:71], v[98:99] op_sel_hi:[1,0]
	s_waitcnt lgkmcnt(3)
	v_pk_add_f32 v[74:75], v[74:75], 1.0 op_sel_hi:[1,0]
	v_bfe_u32 v95, v93, 16, 1
	s_waitcnt lgkmcnt(1)
	v_pk_fma_f32 v[70:71], v[70:71], v[74:75], v[78:79]
	v_pk_mul_f32 v[72:73], v[72:73], v[98:99] op_sel_hi:[1,0]
	v_pk_add_f32 v[74:75], v[76:77], 1.0 op_sel_hi:[1,0]
	v_mov_b32_e32 v78, v193
	v_pk_fma_f32 v[72:73], v[72:73], v[74:75], v[80:81]
	v_add3_u32 v74, v93, v95, s80
	v_and_or_b32 v95, v74, s76, v92
	v_bfe_u32 v74, v70, 16, 1
	v_cvt_pk_fp8_f32 v78, v70, v71
	v_add3_u32 v70, v70, v74, s80
	v_bfe_u32 v74, v71, 16, 1
	v_add3_u32 v71, v71, v74, s80
	v_pk_mul_f32 v[66:67], v[66:67], v[98:99] op_sel_hi:[1,0]
	v_pk_add_f32 v[74:75], v[82:83], 1.0 op_sel_hi:[1,0]
	v_mov_b32_e32 v76, v193
	s_waitcnt lgkmcnt(0)
	v_pk_fma_f32 v[66:67], v[66:67], v[74:75], v[86:87]
	v_lshrrev_b32_e32 v70, 16, v70
	v_cvt_pk_fp8_f32 v76, v66, v67
	v_pk_mul_f32 v[68:69], v[68:69], v[98:99] op_sel_hi:[1,0]
	v_pk_add_f32 v[74:75], v[84:85], 1.0 op_sel_hi:[1,0]
	v_and_or_b32 v70, v71, s76, v70
	v_bfe_u32 v71, v72, 16, 1
	v_pk_fma_f32 v[68:69], v[68:69], v[74:75], v[88:89]
	v_cvt_pk_fp8_f32 v78, v72, v73 op_sel:[0,0,1]
	v_add3_u32 v71, v72, v71, s80
	v_bfe_u32 v72, v73, 16, 1
	v_cvt_pk_fp8_f32 v76, v68, v69 op_sel:[0,0,1]
	v_lshrrev_b32_e32 v71, 16, v71
	v_add3_u32 v72, v73, v72, s80
	v_and_or_b32 v71, v72, s76, v71
	global_store_dwordx2 v[90:91], v[94:95], off offset:2560 sc1
	global_store_dword v[100:101], v78, off offset:3584 sc1
	global_store_dwordx2 v[90:91], v[70:71], off offset:3072 sc1
	global_store_dword v[100:101], v76, off offset:3840 sc1
	v_bfe_u32 v70, v66, 16, 1
	v_add3_u32 v66, v66, v70, s80
	v_bfe_u32 v70, v67, 16, 1
	v_lshrrev_b32_e32 v66, 16, v66
	v_add3_u32 v67, v67, v70, s80
	v_and_or_b32 v66, v67, s76, v66
	v_bfe_u32 v67, v68, 16, 1
	v_add3_u32 v67, v68, v67, s80
	v_bfe_u32 v68, v69, 16, 1
	v_lshrrev_b32_e32 v67, 16, v67
	v_add3_u32 v68, v69, v68, s80
	v_and_or_b32 v67, v68, s76, v67
	global_store_dwordx2 v[90:91], v[66:67], off offset:3584 sc1
	s_add_u32 s26, s26, s34
	s_addc_u32 s27, s27, s35
	s_add_u32 s4, s4, s6
	s_addc_u32 s5, s5, s7
	s_add_i32 s69, s69, s74
	s_andn2_b64 vcc, exec, s[52:53]
	s_mov_b32 s46, s50
	s_cbranch_vccz .LBB0_374

.LBB0_868:
	v_add_f32_e32 v130, v126, v127
	v_add_f32_e32 v131, v128, v129
	v_add_f32_e32 v130, v130, v131
	v_and_b32_e32 v131, 64, v241
	v_add_u32_e32 v131, 64, v131
	v_xor_b32_e32 v132, 1, v241
	v_cmp_lt_i32_e32 vcc, v132, v131
	v_add_f32_e32 v130, v242, v130
	s_and_b32 s2, s19, 0xffff8000
	v_cndmask_b32_e32 v132, v241, v132, vcc
	v_lshlrev_b32_e32 v185, 2, v132
	ds_bpermute_b32 v132, v185, v130
	s_add_i32 s2, s2, 0x8000
	s_waitcnt lgkmcnt(0)
	v_add_f32_e32 v130, v130, v132
	v_xor_b32_e32 v132, 2, v241
	v_cmp_lt_i32_e32 vcc, v132, v131
	s_nop 1
	v_cndmask_b32_e32 v132, v241, v132, vcc
	v_lshlrev_b32_e32 v190, 2, v132
	ds_bpermute_b32 v132, v190, v130
	s_waitcnt lgkmcnt(0)
	v_add_f32_e32 v130, v130, v132
	v_xor_b32_e32 v132, 4, v241
	v_cmp_lt_i32_e32 vcc, v132, v131
	s_nop 1
	v_cndmask_b32_e32 v132, v241, v132, vcc
	v_lshlrev_b32_e32 v191, 2, v132
	ds_bpermute_b32 v132, v191, v130
	s_waitcnt lgkmcnt(0)
	v_add_f32_e32 v130, v130, v132
	v_xor_b32_e32 v132, 8, v241
	v_cmp_lt_i32_e32 vcc, v132, v131
	s_nop 1
	v_cndmask_b32_e32 v132, v241, v132, vcc
	v_lshlrev_b32_e32 v192, 2, v132
	ds_bpermute_b32 v132, v192, v130
	s_waitcnt lgkmcnt(0)
	v_add_f32_e32 v130, v130, v132
	v_xor_b32_e32 v132, 16, v241
	v_cmp_lt_i32_e32 vcc, v132, v131
	s_nop 1
	v_cndmask_b32_e32 v132, v241, v132, vcc
	v_lshlrev_b32_e32 v193, 2, v132
	ds_bpermute_b32 v132, v193, v130
	s_waitcnt lgkmcnt(0)
	v_add_f32_e32 v130, v130, v132
	v_xor_b32_e32 v132, 32, v241
	v_cmp_lt_i32_e32 vcc, v132, v131
	s_nop 1
	v_cndmask_b32_e32 v131, v241, v132, vcc
	v_lshlrev_b32_e32 v194, 2, v131
	ds_bpermute_b32 v131, v194, v130
	s_waitcnt lgkmcnt(0)
	v_add_f32_e32 v182, v130, v131
	v_fmamk_f32 v87, v182, 0xb9800000, v87
	v_fmamk_f32 v86, v182, 0xb9800000, v86
	v_fmamk_f32 v89, v182, 0xb9800000, v89
	v_fmac_f32_e32 v88, 0xb9800000, v182
	v_pk_mul_f32 v[130:131], v[88:89], v[88:89]
	v_pk_mul_f32 v[132:133], v[86:87], v[86:87]
	v_fmamk_f32 v189, v182, 0xb9800000, v79
	v_pk_mov_b32 v[134:135], v[132:133], v[130:131] op_sel:[1,0]
	v_mov_b32_e32 v133, v131
	v_fmamk_f32 v188, v182, 0xb9800000, v78
	v_fmamk_f32 v81, v182, 0xb9800000, v81
	v_fmac_f32_e32 v80, 0xb9800000, v182
	v_pk_add_f32 v[130:131], v[134:135], v[132:133]
	v_pk_mul_f32 v[78:79], v[80:81], v[80:81]
	v_pk_mul_f32 v[132:133], v[188:189], v[188:189]
	v_fmac_f32_e32 v76, 0xb9800000, v182
	v_pk_mov_b32 v[134:135], v[132:133], v[78:79] op_sel:[1,0]
	v_mov_b32_e32 v133, v79
	v_pk_add_f32 v[78:79], v[134:135], v[132:133]
	v_fmamk_f32 v77, v182, 0xb9800000, v77
	v_pk_add_f32 v[132:133], v[78:79], v[78:79] op_sel_hi:[0,1]
	v_fmamk_f32 v78, v182, 0xb9800000, v74
	v_fmamk_f32 v79, v182, 0xb9800000, v75
	v_mul_f32_e32 v74, v78, v78
	v_pk_fma_f32 v[134:135], v[78:79], v[78:79], v[74:75] op_sel_hi:[1,1,0]
	v_mul_f32_e32 v74, v76, v76
	v_pk_add_f32 v[130:131], v[130:131], v[130:131] op_sel_hi:[0,1]
	v_pk_fma_f32 v[136:137], v[76:77], v[76:77], v[74:75] op_sel_hi:[1,1,0]
	v_fmamk_f32 v75, v182, 0xb9800000, v85
	v_fmamk_f32 v74, v182, 0xb9800000, v84
	v_fmamk_f32 v83, v182, 0xb9800000, v83
	v_fmac_f32_e32 v82, 0xb9800000, v182
	v_mul_f32_e32 v134, v82, v82
	v_mul_f32_e32 v136, v83, v83
	v_mul_f32_e32 v130, v74, v74
	v_mul_f32_e32 v132, v75, v75
	v_pk_add_f32 v[84:85], v[134:135], v[136:137]
	v_pk_add_f32 v[130:131], v[130:131], v[132:133]
	v_fmamk_f32 v71, v182, 0xb9800000, v71
	v_fmamk_f32 v70, v182, 0xb9800000, v70
	v_fmamk_f32 v73, v182, 0xb9800000, v73
	v_fmac_f32_e32 v72, 0xb9800000, v182
	v_fmamk_f32 v186, v182, 0xb9800000, v66
	v_pk_add_f32 v[84:85], v[84:85], v[130:131]
	v_pk_mul_f32 v[130:131], v[72:73], v[72:73]
	v_pk_mul_f32 v[132:133], v[70:71], v[70:71]
	v_fmamk_f32 v187, v182, 0xb9800000, v67
	v_mul_f32_e32 v66, v186, v186
	v_pk_mov_b32 v[134:135], v[132:133], v[130:131] op_sel:[1,0]
	v_mov_b32_e32 v133, v131
	v_fmac_f32_e32 v68, 0xb9800000, v182
	v_pk_fma_f32 v[66:67], v[186:187], v[186:187], v[66:67] op_sel_hi:[1,1,0]
	v_pk_add_f32 v[130:131], v[134:135], v[132:133]
	v_fmamk_f32 v69, v182, 0xb9800000, v69
	v_mul_f32_e32 v66, v68, v68
	v_pk_add_f32 v[84:85], v[84:85], v[84:85] op_sel_hi:[0,1]
	v_pk_add_f32 v[130:131], v[130:131], v[130:131] op_sel_hi:[0,1]
	v_pk_fma_f32 v[132:133], v[68:69], v[68:69], v[66:67] op_sel_hi:[1,1,0]
	v_fmamk_f32 v139, v182, 0xb9800000, v93
	v_fmamk_f32 v138, v182, 0xb9800000, v92
	v_fmamk_f32 v91, v182, 0xb9800000, v91
	v_fmac_f32_e32 v90, 0xb9800000, v182
	v_mul_f32_e32 v66, v90, v90
	v_mul_f32_e32 v132, v91, v91
	v_mul_f32_e32 v130, v138, v138
	v_mul_f32_e32 v84, v139, v139
	v_pk_add_f32 v[66:67], v[66:67], v[132:133]
	v_pk_add_f32 v[84:85], v[130:131], v[84:85]
	v_fmamk_f32 v135, v182, 0xb9800000, v95
	v_pk_add_f32 v[66:67], v[66:67], v[84:85]
	v_fmamk_f32 v134, v182, 0xb9800000, v94
	v_fmamk_f32 v97, v182, 0xb9800000, v97
	v_fmac_f32_e32 v96, 0xb9800000, v182
	v_pk_add_f32 v[84:85], v[66:67], v[66:67] op_sel_hi:[0,1]
	v_pk_mul_f32 v[66:67], v[96:97], v[96:97]
	v_pk_mul_f32 v[92:93], v[134:135], v[134:135]
	v_fmac_f32_e32 v100, 0xb9800000, v182
	v_pk_mov_b32 v[94:95], v[92:93], v[66:67] op_sel:[1,0]
	v_mov_b32_e32 v93, v67
	v_pk_add_f32 v[66:67], v[94:95], v[92:93]
	v_fmamk_f32 v101, v182, 0xb9800000, v101
	v_pk_add_f32 v[92:93], v[66:67], v[66:67] op_sel_hi:[0,1]
	v_fmamk_f32 v66, v182, 0xb9800000, v98
	v_fmamk_f32 v67, v182, 0xb9800000, v99
	v_mul_f32_e32 v84, v66, v66
	v_pk_fma_f32 v[94:95], v[66:67], v[66:67], v[84:85] op_sel_hi:[1,1,0]
	v_mul_f32_e32 v84, v100, v100
	v_pk_fma_f32 v[98:99], v[100:101], v[100:101], v[84:85] op_sel_hi:[1,1,0]
	v_fmamk_f32 v131, v182, 0xb9800000, v113
	v_fmamk_f32 v130, v182, 0xb9800000, v112
	v_fmamk_f32 v111, v182, 0xb9800000, v111
	v_fmac_f32_e32 v110, 0xb9800000, v182
	v_mul_f32_e32 v94, v110, v110
	v_mul_f32_e32 v98, v111, v111
	v_mul_f32_e32 v92, v130, v130
	v_mul_f32_e32 v84, v131, v131
	v_pk_add_f32 v[94:95], v[94:95], v[98:99]
	v_pk_add_f32 v[84:85], v[92:93], v[84:85]
	v_fmamk_f32 v107, v182, 0xb9800000, v107
	v_pk_add_f32 v[84:85], v[94:95], v[84:85]
	v_fmamk_f32 v106, v182, 0xb9800000, v106
	v_fmamk_f32 v109, v182, 0xb9800000, v109
	v_fmac_f32_e32 v108, 0xb9800000, v182
	v_pk_add_f32 v[84:85], v[84:85], v[84:85] op_sel_hi:[0,1]
	v_pk_mul_f32 v[92:93], v[108:109], v[108:109]
	v_pk_mul_f32 v[94:95], v[106:107], v[106:107]
	v_fmamk_f32 v102, v182, 0xb9800000, v102
	v_pk_mov_b32 v[98:99], v[94:95], v[92:93] op_sel:[1,0]
	v_mov_b32_e32 v95, v93
	v_fmamk_f32 v103, v182, 0xb9800000, v103
	v_fmac_f32_e32 v104, 0xb9800000, v182
	v_mul_f32_e32 v84, v102, v102
	v_pk_add_f32 v[92:93], v[98:99], v[94:95]
	v_fmamk_f32 v105, v182, 0xb9800000, v105
	v_pk_fma_f32 v[94:95], v[102:103], v[102:103], v[84:85] op_sel_hi:[1,1,0]
	v_mul_f32_e32 v84, v104, v104
	v_pk_add_f32 v[92:93], v[92:93], v[92:93] op_sel_hi:[0,1]
	v_pk_fma_f32 v[98:99], v[104:105], v[104:105], v[84:85] op_sel_hi:[1,1,0]
	v_fmamk_f32 v133, v182, 0xb9800000, v125
	v_fmamk_f32 v132, v182, 0xb9800000, v124
	v_fmamk_f32 v123, v182, 0xb9800000, v123
	v_fmac_f32_e32 v122, 0xb9800000, v182
	v_mul_f32_e32 v94, v122, v122
	v_mul_f32_e32 v98, v123, v123
	v_mul_f32_e32 v92, v132, v132
	v_mul_f32_e32 v84, v133, v133
	v_pk_add_f32 v[94:95], v[94:95], v[98:99]
	v_pk_add_f32 v[84:85], v[92:93], v[84:85]
	v_fmamk_f32 v137, v182, 0xb9800000, v115
	v_pk_add_f32 v[84:85], v[94:95], v[84:85]
	v_fmamk_f32 v136, v182, 0xb9800000, v114
	v_fmamk_f32 v117, v182, 0xb9800000, v117
	v_fmac_f32_e32 v116, 0xb9800000, v182
	v_pk_add_f32 v[84:85], v[84:85], v[84:85] op_sel_hi:[0,1]
	v_pk_mul_f32 v[92:93], v[116:117], v[116:117]
	v_pk_mul_f32 v[94:95], v[136:137], v[136:137]
	v_fmamk_f32 v124, v182, 0xb9800000, v118
	v_pk_mov_b32 v[98:99], v[94:95], v[92:93] op_sel:[1,0]
	v_mov_b32_e32 v95, v93
	v_fmamk_f32 v125, v182, 0xb9800000, v119
	v_fmac_f32_e32 v120, 0xb9800000, v182
	v_mul_f32_e32 v84, v124, v124
	v_pk_add_f32 v[92:93], v[98:99], v[94:95]
	v_fmamk_f32 v121, v182, 0xb9800000, v121
	v_pk_fma_f32 v[94:95], v[124:125], v[124:125], v[84:85] op_sel_hi:[1,1,0]
	v_mul_f32_e32 v84, v120, v120
	v_pk_add_f32 v[92:93], v[92:93], v[92:93] op_sel_hi:[0,1]
	v_pk_fma_f32 v[98:99], v[120:121], v[120:121], v[84:85] op_sel_hi:[1,1,0]
	v_fmamk_f32 v119, v182, 0xb9800000, v129
	v_fmamk_f32 v118, v182, 0xb9800000, v128
	v_fmamk_f32 v127, v182, 0xb9800000, v127
	v_fmac_f32_e32 v126, 0xb9800000, v182
	v_mul_f32_e32 v94, v126, v126
	v_mul_f32_e32 v98, v127, v127
	v_mul_f32_e32 v92, v118, v118
	v_mul_f32_e32 v84, v119, v119
	v_pk_add_f32 v[94:95], v[94:95], v[98:99]
	v_pk_add_f32 v[84:85], v[92:93], v[84:85]
	v_lshl_add_u64 v[182:183], s[40:41], 0, v[180:181]
	v_pk_add_f32 v[84:85], v[94:95], v[84:85]
	s_nop 0
	v_add_f32_e32 v84, v84, v85
	ds_bpermute_b32 v85, v185, v84
	s_waitcnt lgkmcnt(0)
	v_add_f32_e32 v84, v84, v85
	ds_bpermute_b32 v85, v190, v84
	s_waitcnt lgkmcnt(0)
	v_add_f32_e32 v84, v84, v85
	ds_bpermute_b32 v85, v191, v84
	s_waitcnt lgkmcnt(0)
	v_add_f32_e32 v84, v84, v85
	ds_bpermute_b32 v85, v192, v84
	s_waitcnt lgkmcnt(0)
	v_add_f32_e32 v84, v84, v85
	ds_bpermute_b32 v85, v193, v84
	s_waitcnt lgkmcnt(0)
	v_add_f32_e32 v84, v84, v85
	ds_bpermute_b32 v85, v194, v84
	s_waitcnt lgkmcnt(0)
	v_add_f32_e32 v84, v84, v85
	v_fmamk_f32 v84, v84, 0x39800000, v179
	v_mul_f32_e32 v85, 0x4f800000, v84
	v_cmp_gt_f32_e32 vcc, s48, v84
	s_nop 1
	v_cndmask_b32_e32 v84, v84, v85, vcc
	v_sqrt_f32_e32 v85, v84
	s_nop 0
	v_add_u32_e32 v92, -1, v85
	v_fma_f32 v93, -v92, v85, v84
	v_cmp_ge_f32_e64 s[0:1], 0, v93
	v_add_u32_e32 v93, 1, v85
	s_nop 0
	v_cndmask_b32_e64 v92, v85, v92, s[0:1]
	v_fma_f32 v85, -v93, v85, v84
	v_cmp_lt_f32_e64 s[0:1], 0, v85
	s_nop 1
	v_cndmask_b32_e64 v85, v92, v93, s[0:1]
	v_mul_f32_e32 v92, 0x37800000, v85
	v_cndmask_b32_e32 v85, v85, v92, vcc
	v_cmp_class_f32_e32 vcc, v84, v237
	s_nop 1
	v_cndmask_b32_e32 v84, v85, v84, vcc
	v_div_scale_f32 v85, s[0:1], v84, v84, 1.0
	v_rcp_f32_e32 v92, v85
	s_nop 0
	v_fma_f32 v93, -v85, v92, 1.0
	v_fmac_f32_e32 v92, v93, v92
	v_div_scale_f32 v93, vcc, 1.0, v84, 1.0
	v_mul_f32_e32 v94, v93, v92
	v_fma_f32 v95, -v85, v94, v93
	v_fmac_f32_e32 v94, v95, v92
	v_fma_f32 v85, -v85, v94, v93
	v_div_fmas_f32 v85, v85, v92, v94
	ds_read_b128 v[92:95], v236
	ds_read_b128 v[112:115], v236 offset:16384
	v_div_fixup_f32 v184, v85, v84, 1.0
	ds_read_b128 v[196:199], v236 offset:17408
	ds_read_b128 v[200:203], v236 offset:1024
	v_pk_mul_f32 v[88:89], v[88:89], v[184:185] op_sel_hi:[1,0]
	v_pk_mul_f32 v[84:85], v[86:87], v[184:185] op_sel_hi:[1,0]
	s_waitcnt lgkmcnt(2)
	v_pk_fma_f32 v[86:87], v[94:95], v[88:89], v[114:115]
	v_pk_fma_f32 v[84:85], v[92:93], v[84:85], v[112:113]
	v_mov_b32_e32 v93, v87
	v_pk_mov_b32 v[88:89], v[84:85], v[86:87] op_sel:[1,0]
	v_mov_b32_e32 v92, v84
	v_pk_add_f32 v[88:89], v[88:89], v[92:93]
	v_pk_mul_f32 v[80:81], v[80:81], v[184:185] op_sel_hi:[1,0]
	v_pk_mul_f32 v[92:93], v[188:189], v[184:185] op_sel_hi:[1,0]
	s_waitcnt lgkmcnt(0)
	v_pk_fma_f32 v[94:95], v[202:203], v[80:81], v[198:199]
	v_pk_fma_f32 v[92:93], v[200:201], v[92:93], v[196:197]
	global_store_dwordx4 v180, v[84:87], s[40:41] sc1 nt
	global_store_dwordx4 v180, v[92:95], s[40:41] offset:1024 sc1 nt
	ds_read_b128 v[112:115], v236 offset:18432
	ds_read_b128 v[196:199], v236 offset:2048
	ds_read_b128 v[200:203], v236 offset:19456
	ds_read_b128 v[204:207], v236 offset:3072
	v_pk_mov_b32 v[80:81], v[92:93], v[94:95] op_sel:[1,0]
	v_mov_b32_e32 v98, v92
	v_mov_b32_e32 v99, v95
	v_pk_add_f32 v[80:81], v[80:81], v[98:99]
	v_pk_mul_f32 v[76:77], v[76:77], v[184:185] op_sel_hi:[1,0]
	v_pk_mul_f32 v[78:79], v[78:79], v[184:185] op_sel_hi:[1,0]
	v_pk_mul_f32 v[82:83], v[82:83], v[184:185] op_sel_hi:[1,0]
	v_pk_mul_f32 v[74:75], v[74:75], v[184:185] op_sel_hi:[1,0]
	v_pk_add_f32 v[98:99], v[80:81], v[80:81] op_sel_hi:[0,1]
	s_waitcnt lgkmcnt(2)
	v_pk_fma_f32 v[78:79], v[196:197], v[78:79], v[112:113]
	v_pk_fma_f32 v[80:81], v[198:199], v[76:77], v[114:115]
	s_waitcnt lgkmcnt(0)
	v_pk_fma_f32 v[76:77], v[206:207], v[74:75], v[202:203]
	v_pk_fma_f32 v[74:75], v[204:205], v[82:83], v[200:201]
	global_store_dwordx4 v180, v[78:81], s[40:41] offset:2048 sc1 nt
	global_store_dwordx4 v180, v[74:77], s[40:41] offset:3072 sc1 nt
	v_add_f32_e32 v113, v78, v79
	v_add_f32_e32 v115, v80, v81
	v_mov_b32_e32 v112, v74
	v_mov_b32_e32 v114, v75
	v_pk_add_f32 v[82:83], v[112:113], v[114:115]
	ds_read_b128 v[112:115], v236 offset:4096
	ds_read_b128 v[196:199], v236 offset:20480
	v_add_f32_e32 v88, v88, v89
	v_add_f32_e32 v89, 0, v88
	v_mov_b32_e32 v98, v76
	v_mov_b32_e32 v88, v77
	v_pk_mul_f32 v[70:71], v[70:71], v[184:185] op_sel_hi:[1,0]
	v_pk_mul_f32 v[72:73], v[72:73], v[184:185] op_sel_hi:[1,0]
	ds_read_b128 v[200:203], v236 offset:21504
	ds_read_b128 v[204:207], v236 offset:5120
	v_pk_add_f32 v[88:89], v[98:99], v[88:89]
	s_waitcnt lgkmcnt(2)
	v_pk_fma_f32 v[72:73], v[114:115], v[72:73], v[198:199]
	v_pk_fma_f32 v[70:71], v[112:113], v[70:71], v[196:197]
	v_pk_add_f32 v[82:83], v[82:83], v[88:89]
	v_add_co_u32_e32 v128, vcc, s46, v182
	v_pk_mov_b32 v[88:89], v[70:71], v[72:73] op_sel:[1,0]
	v_mov_b32_e32 v98, v70
	v_mov_b32_e32 v99, v73
	v_addc_co_u32_e32 v129, vcc, 0, v183, vcc
	v_pk_add_f32 v[88:89], v[88:89], v[98:99]
	v_add_co_u32_e32 v208, vcc, s45, v182
	v_pk_add_f32 v[98:99], v[88:89], v[88:89] op_sel_hi:[0,1]
	v_pk_mul_f32 v[88:89], v[186:187], v[184:185] op_sel_hi:[1,0]
	v_pk_mul_f32 v[68:69], v[68:69], v[184:185] op_sel_hi:[1,0]
	v_addc_co_u32_e32 v209, vcc, 0, v183, vcc
	s_waitcnt lgkmcnt(0)
	v_pk_fma_f32 v[114:115], v[206:207], v[68:69], v[202:203]
	v_pk_fma_f32 v[112:113], v[204:205], v[88:89], v[200:201]
	global_store_dwordx4 v[208:209], v[70:73], off offset:-4096 sc1 nt
	global_store_dwordx4 v[128:129], v[112:115], off offset:1024 sc1 nt
	ds_read_b128 v[186:189], v236 offset:22528
	ds_read_b128 v[196:199], v236 offset:6144
	v_pk_mul_f32 v[88:89], v[90:91], v[184:185] op_sel_hi:[1,0]
	v_pk_mul_f32 v[90:91], v[138:139], v[184:185] op_sel_hi:[1,0]
	v_pk_add_f32 v[82:83], v[82:83], v[82:83] op_sel_hi:[0,1]
	ds_read_b128 v[200:203], v236 offset:23552
	ds_read_b128 v[204:207], v236 offset:7168
	s_waitcnt lgkmcnt(2)
	v_pk_fma_f32 v[90:91], v[198:199], v[90:91], v[188:189]
	v_pk_fma_f32 v[88:89], v[196:197], v[88:89], v[186:187]
	v_add_f32_e32 v69, v112, v113
	v_add_f32_e32 v211, v114, v115
	v_mov_b32_e32 v68, v88
	v_mov_b32_e32 v210, v89
	v_mov_b32_e32 v98, v90
	v_mov_b32_e32 v82, v91
	v_pk_add_f32 v[68:69], v[68:69], v[210:211]
	v_pk_add_f32 v[82:83], v[98:99], v[82:83]
	v_pk_mul_f32 v[96:97], v[96:97], v[184:185] op_sel_hi:[1,0]
	v_pk_add_f32 v[68:69], v[68:69], v[82:83]
	s_waitcnt lgkmcnt(0)
	v_pk_fma_f32 v[98:99], v[206:207], v[96:97], v[202:203]
	v_pk_add_f32 v[82:83], v[68:69], v[68:69] op_sel_hi:[0,1]
	v_pk_mul_f32 v[68:69], v[134:135], v[184:185] op_sel_hi:[1,0]
	global_store_dwordx4 v[128:129], v[88:91], off offset:2048 sc1 nt
	v_pk_fma_f32 v[96:97], v[204:205], v[68:69], v[200:201]
	global_store_dwordx4 v[128:129], v[96:99], off offset:3072 sc1 nt
	ds_read_b128 v[186:189], v236 offset:8192
	ds_read_b128 v[196:199], v236 offset:24576
	ds_read_b128 v[200:203], v236 offset:25600
	ds_read_b128 v[204:207], v236 offset:9216
	v_pk_mov_b32 v[68:69], v[96:97], v[98:99] op_sel:[1,0]
	v_mov_b32_e32 v128, v96
	v_mov_b32_e32 v129, v99
	v_pk_add_f32 v[68:69], v[68:69], v[128:129]
	v_pk_mul_f32 v[66:67], v[66:67], v[184:185] op_sel_hi:[1,0]
	v_pk_add_f32 v[134:135], v[68:69], v[68:69] op_sel_hi:[0,1]
	v_pk_mul_f32 v[68:69], v[100:101], v[184:185] op_sel_hi:[1,0]
	v_pk_mul_f32 v[110:111], v[110:111], v[184:185] op_sel_hi:[1,0]
	v_pk_mul_f32 v[128:129], v[130:131], v[184:185] op_sel_hi:[1,0]
	s_waitcnt lgkmcnt(2)
	v_pk_fma_f32 v[68:69], v[188:189], v[68:69], v[198:199]
	v_pk_fma_f32 v[66:67], v[186:187], v[66:67], v[196:197]
	s_waitcnt lgkmcnt(0)
	v_pk_fma_f32 v[130:131], v[206:207], v[128:129], v[202:203]
	v_pk_fma_f32 v[128:129], v[204:205], v[110:111], v[200:201]
	global_store_dwordx4 v[208:209], v[66:69], off sc1 nt
	global_store_dwordx4 v[208:209], v[128:131], off offset:1024 sc1 nt
	ds_read_b128 v[186:189], v236 offset:26624
	ds_read_b128 v[196:199], v236 offset:10240
	v_add_f32_e32 v101, v66, v67
	v_add_f32_e32 v139, v68, v69
	v_mov_b32_e32 v100, v128
	v_mov_b32_e32 v138, v129
	v_mov_b32_e32 v134, v130
	v_mov_b32_e32 v82, v131
	v_pk_add_f32 v[100:101], v[100:101], v[138:139]
	v_pk_add_f32 v[82:83], v[134:135], v[82:83]
	ds_read_b128 v[200:203], v236 offset:27648
	ds_read_b128 v[204:207], v236 offset:11264
	v_pk_add_f32 v[82:83], v[100:101], v[82:83]
	v_pk_mul_f32 v[100:101], v[106:107], v[184:185] op_sel_hi:[1,0]
	v_pk_mul_f32 v[106:107], v[108:109], v[184:185] op_sel_hi:[1,0]
	v_pk_mul_f32 v[122:123], v[122:123], v[184:185] op_sel_hi:[1,0]
	s_waitcnt lgkmcnt(2)
	v_pk_fma_f32 v[108:109], v[106:107], v[198:199], v[188:189]
	v_pk_fma_f32 v[106:107], v[100:101], v[196:197], v[186:187]
	v_mov_b32_e32 v111, v109
	v_pk_mov_b32 v[100:101], v[106:107], v[108:109] op_sel:[1,0]
	v_mov_b32_e32 v110, v106
	v_pk_add_f32 v[100:101], v[100:101], v[110:111]
	global_store_dwordx4 v[208:209], v[106:109], off offset:2048 sc1 nt
	v_pk_add_f32 v[110:111], v[100:101], v[100:101] op_sel_hi:[0,1]
	v_pk_mul_f32 v[100:101], v[102:103], v[184:185] op_sel_hi:[1,0]
	v_pk_mul_f32 v[102:103], v[104:105], v[184:185] op_sel_hi:[1,0]
	s_waitcnt lgkmcnt(0)
	v_pk_fma_f32 v[100:101], v[100:101], v[204:205], v[200:201]
	v_pk_fma_f32 v[102:103], v[102:103], v[206:207], v[202:203]
	global_store_dwordx4 v[208:209], v[100:103], off offset:3072 sc1 nt
	ds_read_b128 v[186:189], v236 offset:12288
	ds_read_b128 v[196:199], v236 offset:28672
	v_pk_mul_f32 v[132:133], v[132:133], v[184:185] op_sel_hi:[1,0]
	ds_read_b128 v[200:203], v236 offset:29696
	ds_read_b128 v[204:207], v236 offset:13312
	v_pk_add_f32 v[82:83], v[82:83], v[82:83] op_sel_hi:[0,1]
	v_add_f32_e32 v105, v100, v101
	s_waitcnt lgkmcnt(2)
	v_pk_fma_f32 v[134:135], v[132:133], v[188:189], v[198:199]
	v_pk_fma_f32 v[132:133], v[122:123], v[186:187], v[196:197]
	v_add_f32_e32 v139, v102, v103
	v_mov_b32_e32 v104, v132
	v_mov_b32_e32 v138, v133
	v_mov_b32_e32 v110, v134
	v_mov_b32_e32 v82, v135
	v_pk_add_f32 v[104:105], v[104:105], v[138:139]
	v_pk_add_f32 v[82:83], v[110:111], v[82:83]
	v_pk_mul_f32 v[110:111], v[116:117], v[184:185] op_sel_hi:[1,0]
	v_pk_add_f32 v[82:83], v[104:105], v[82:83]
	v_pk_mul_f32 v[104:105], v[136:137], v[184:185] op_sel_hi:[1,0]
	ds_read_b128 v[186:189], v236 offset:30720
	ds_read_b128 v[196:199], v236 offset:14336
	s_waitcnt lgkmcnt(2)
	v_pk_fma_f32 v[138:139], v[110:111], v[206:207], v[202:203]
	v_pk_fma_f32 v[136:137], v[104:105], v[204:205], v[200:201]
	ds_read_b128 v[200:203], v236 offset:31744
	ds_read_b128 v[204:207], v236 offset:15360
	v_pk_mov_b32 v[104:105], v[136:137], v[138:139] op_sel:[1,0]
	v_mov_b32_e32 v110, v136
	v_mov_b32_e32 v111, v139
	v_pk_mul_f32 v[116:117], v[120:121], v[184:185] op_sel_hi:[1,0]
	v_pk_add_f32 v[104:105], v[104:105], v[110:111]
	v_pk_mul_f32 v[110:111], v[124:125], v[184:185] op_sel_hi:[1,0]
	s_waitcnt lgkmcnt(2)
	v_pk_fma_f32 v[122:123], v[116:117], v[198:199], v[188:189]
	v_pk_mul_f32 v[116:117], v[126:127], v[184:185] op_sel_hi:[1,0]
	v_pk_mul_f32 v[118:119], v[118:119], v[184:185] op_sel_hi:[1,0]
	v_pk_add_f32 v[82:83], v[82:83], v[82:83] op_sel:[0,1] op_sel_hi:[1,0]
	v_pk_add_f32 v[104:105], v[104:105], v[104:105] op_sel:[0,1] op_sel_hi:[1,0]
	v_pk_fma_f32 v[120:121], v[110:111], v[196:197], v[186:187]
	s_waitcnt lgkmcnt(0)
	v_pk_fma_f32 v[118:119], v[118:119], v[206:207], v[202:203]
	v_pk_fma_f32 v[116:117], v[116:117], v[204:205], v[200:201]
	v_add_f32_e32 v110, v120, v121
	v_add_f32_e32 v124, v122, v123
	v_mov_b32_e32 v105, v116
	v_mov_b32_e32 v83, v117
	v_mov_b32_e32 v111, v118
	v_mov_b32_e32 v125, v119
	v_pk_add_f32 v[82:83], v[104:105], v[82:83]
	v_pk_add_f32 v[104:105], v[110:111], v[124:125]
	s_nop 0
	v_pk_add_f32 v[82:83], v[82:83], v[104:105]
	s_nop 0
	v_add_f32_e32 v82, v82, v83
	ds_bpermute_b32 v83, v185, v82
	s_waitcnt lgkmcnt(0)
	v_add_f32_e32 v82, v82, v83
	ds_bpermute_b32 v83, v190, v82
	s_waitcnt lgkmcnt(0)
	v_add_f32_e32 v82, v82, v83
	ds_bpermute_b32 v83, v191, v82
	s_waitcnt lgkmcnt(0)
	v_add_f32_e32 v82, v82, v83
	ds_bpermute_b32 v83, v192, v82
	s_waitcnt lgkmcnt(0)
	v_add_f32_e32 v104, v82, v83
	ds_bpermute_b32 v105, v193, v104
	v_add_co_u32_e32 v82, vcc, s47, v182
	s_waitcnt lgkmcnt(0)
	v_add_f32_e32 v104, v104, v105
	ds_bpermute_b32 v105, v194, v104
	v_addc_co_u32_e32 v83, vcc, 0, v183, vcc
	global_store_dwordx4 v[82:83], v[132:135], off sc1 nt
	global_store_dwordx4 v[82:83], v[136:139], off offset:1024 sc1 nt
	global_store_dwordx4 v[82:83], v[120:123], off offset:2048 sc1 nt
	global_store_dwordx4 v[82:83], v[116:119], off offset:3072 sc1 nt
	s_waitcnt lgkmcnt(0)
	v_add_f32_e32 v126, v104, v105
	v_fmamk_f32 v85, v126, 0xb9800000, v85
	v_fmac_f32_e32 v84, 0xb9800000, v126
	v_fmamk_f32 v87, v126, 0xb9800000, v87
	v_fmac_f32_e32 v86, 0xb9800000, v126
	v_pk_mul_f32 v[82:83], v[86:87], v[86:87]
	v_pk_mul_f32 v[104:105], v[84:85], v[84:85]
	v_fmamk_f32 v93, v126, 0xb9800000, v93
	v_pk_mov_b32 v[110:111], v[104:105], v[82:83] op_sel:[1,0]
	v_mov_b32_e32 v105, v83
	v_pk_add_f32 v[82:83], v[110:111], v[104:105]
	v_fmac_f32_e32 v92, 0xb9800000, v126
	v_fmamk_f32 v95, v126, 0xb9800000, v95
	v_fmac_f32_e32 v94, 0xb9800000, v126
	v_pk_add_f32 v[82:83], v[82:83], v[82:83] op_sel_hi:[0,1]
	v_pk_mul_f32 v[104:105], v[94:95], v[94:95]
	v_pk_mul_f32 v[110:111], v[92:93], v[92:93]
	v_fmac_f32_e32 v78, 0xb9800000, v126
	v_pk_mov_b32 v[124:125], v[110:111], v[104:105] op_sel:[1,0]
	v_mov_b32_e32 v111, v105
	v_fmamk_f32 v79, v126, 0xb9800000, v79
	v_fmac_f32_e32 v80, 0xb9800000, v126
	v_mul_f32_e32 v82, v78, v78
	v_pk_add_f32 v[104:105], v[124:125], v[110:111]
	v_fmamk_f32 v81, v126, 0xb9800000, v81
	v_pk_fma_f32 v[110:111], v[78:79], v[78:79], v[82:83] op_sel_hi:[1,1,0]
	v_mul_f32_e32 v82, v80, v80
	v_pk_add_f32 v[104:105], v[104:105], v[104:105] op_sel_hi:[0,1]
	v_pk_fma_f32 v[124:125], v[80:81], v[80:81], v[82:83] op_sel_hi:[1,1,0]
	v_fmamk_f32 v77, v126, 0xb9800000, v77
	v_fmac_f32_e32 v76, 0xb9800000, v126
	v_fmamk_f32 v75, v126, 0xb9800000, v75
	v_fmac_f32_e32 v74, 0xb9800000, v126
	v_mul_f32_e32 v110, v74, v74
	v_mul_f32_e32 v124, v75, v75
	v_mul_f32_e32 v82, v76, v76
	v_mul_f32_e32 v104, v77, v77
	v_pk_add_f32 v[110:111], v[110:111], v[124:125]
	v_pk_add_f32 v[82:83], v[82:83], v[104:105]
	v_fmamk_f32 v71, v126, 0xb9800000, v71
	v_pk_add_f32 v[82:83], v[110:111], v[82:83]
	v_fmac_f32_e32 v70, 0xb9800000, v126
	v_fmamk_f32 v73, v126, 0xb9800000, v73
	v_fmac_f32_e32 v72, 0xb9800000, v126
	v_pk_add_f32 v[82:83], v[82:83], v[82:83] op_sel_hi:[0,1]
	v_pk_mul_f32 v[104:105], v[72:73], v[72:73]
	v_pk_mul_f32 v[110:111], v[70:71], v[70:71]
	v_fmac_f32_e32 v112, 0xb9800000, v126
	v_pk_mov_b32 v[124:125], v[110:111], v[104:105] op_sel:[1,0]
	v_mov_b32_e32 v111, v105
	v_fmamk_f32 v113, v126, 0xb9800000, v113
	v_fmac_f32_e32 v114, 0xb9800000, v126
	v_mul_f32_e32 v82, v112, v112
	v_pk_add_f32 v[104:105], v[124:125], v[110:111]
	v_fmamk_f32 v115, v126, 0xb9800000, v115
	v_pk_fma_f32 v[110:111], v[112:113], v[112:113], v[82:83] op_sel_hi:[1,1,0]
	v_mul_f32_e32 v82, v114, v114
	v_pk_add_f32 v[104:105], v[104:105], v[104:105] op_sel_hi:[0,1]
	v_pk_fma_f32 v[124:125], v[114:115], v[114:115], v[82:83] op_sel_hi:[1,1,0]
	v_fmamk_f32 v91, v126, 0xb9800000, v91
	v_fmac_f32_e32 v90, 0xb9800000, v126
	v_fmamk_f32 v89, v126, 0xb9800000, v89
	v_fmac_f32_e32 v88, 0xb9800000, v126
	v_mul_f32_e32 v110, v88, v88
	v_mul_f32_e32 v124, v89, v89
	v_mul_f32_e32 v104, v90, v90
	v_mul_f32_e32 v82, v91, v91
	v_pk_add_f32 v[110:111], v[110:111], v[124:125]
	v_pk_add_f32 v[82:83], v[104:105], v[82:83]
	v_fmamk_f32 v97, v126, 0xb9800000, v97
	v_pk_add_f32 v[82:83], v[110:111], v[82:83]
	v_fmac_f32_e32 v96, 0xb9800000, v126
	v_fmamk_f32 v99, v126, 0xb9800000, v99
	v_fmac_f32_e32 v98, 0xb9800000, v126
	v_pk_add_f32 v[82:83], v[82:83], v[82:83] op_sel_hi:[0,1]
	v_pk_mul_f32 v[104:105], v[98:99], v[98:99]
	v_pk_mul_f32 v[110:111], v[96:97], v[96:97]
	v_fmac_f32_e32 v66, 0xb9800000, v126
	v_pk_mov_b32 v[124:125], v[110:111], v[104:105] op_sel:[1,0]
	v_mov_b32_e32 v111, v105
	v_fmamk_f32 v67, v126, 0xb9800000, v67
	v_fmac_f32_e32 v68, 0xb9800000, v126
	v_mul_f32_e32 v82, v66, v66
	v_pk_add_f32 v[104:105], v[124:125], v[110:111]
	v_fmamk_f32 v69, v126, 0xb9800000, v69
	v_pk_fma_f32 v[110:111], v[66:67], v[66:67], v[82:83] op_sel_hi:[1,1,0]
	v_mul_f32_e32 v82, v68, v68
	v_pk_add_f32 v[104:105], v[104:105], v[104:105] op_sel_hi:[0,1]
	v_pk_fma_f32 v[124:125], v[68:69], v[68:69], v[82:83] op_sel_hi:[1,1,0]
	v_fmamk_f32 v131, v126, 0xb9800000, v131
	v_fmac_f32_e32 v130, 0xb9800000, v126
	v_fmamk_f32 v129, v126, 0xb9800000, v129
	v_fmac_f32_e32 v128, 0xb9800000, v126
	v_mul_f32_e32 v110, v128, v128
	v_mul_f32_e32 v124, v129, v129
	v_mul_f32_e32 v104, v130, v130
	v_mul_f32_e32 v82, v131, v131
	v_pk_add_f32 v[110:111], v[110:111], v[124:125]
	v_pk_add_f32 v[82:83], v[104:105], v[82:83]
	v_fmamk_f32 v107, v126, 0xb9800000, v107
	v_pk_add_f32 v[82:83], v[110:111], v[82:83]
	v_fmac_f32_e32 v106, 0xb9800000, v126
	v_fmamk_f32 v109, v126, 0xb9800000, v109
	v_fmac_f32_e32 v108, 0xb9800000, v126
	v_pk_add_f32 v[82:83], v[82:83], v[82:83] op_sel_hi:[0,1]
	v_pk_mul_f32 v[104:105], v[108:109], v[108:109]
	v_pk_mul_f32 v[110:111], v[106:107], v[106:107]
	v_fmac_f32_e32 v100, 0xb9800000, v126
	v_pk_mov_b32 v[124:125], v[110:111], v[104:105] op_sel:[1,0]
	v_mov_b32_e32 v111, v105
	v_fmamk_f32 v101, v126, 0xb9800000, v101
	v_fmac_f32_e32 v102, 0xb9800000, v126
	v_mul_f32_e32 v82, v100, v100
	v_pk_add_f32 v[104:105], v[124:125], v[110:111]
	v_fmamk_f32 v103, v126, 0xb9800000, v103
	v_pk_fma_f32 v[110:111], v[100:101], v[100:101], v[82:83] op_sel_hi:[1,1,0]
	v_mul_f32_e32 v82, v102, v102
	v_pk_add_f32 v[104:105], v[104:105], v[104:105] op_sel_hi:[0,1]
	v_pk_fma_f32 v[124:125], v[102:103], v[102:103], v[82:83] op_sel_hi:[1,1,0]
	v_fmamk_f32 v135, v126, 0xb9800000, v135
	v_fmac_f32_e32 v134, 0xb9800000, v126
	v_fmamk_f32 v133, v126, 0xb9800000, v133
	v_fmac_f32_e32 v132, 0xb9800000, v126
	v_mul_f32_e32 v110, v132, v132
	v_mul_f32_e32 v124, v133, v133
	v_mul_f32_e32 v104, v134, v134
	v_mul_f32_e32 v82, v135, v135
	v_pk_add_f32 v[110:111], v[110:111], v[124:125]
	v_pk_add_f32 v[82:83], v[104:105], v[82:83]
	v_fmamk_f32 v137, v126, 0xb9800000, v137
	v_pk_add_f32 v[82:83], v[110:111], v[82:83]
	v_fmac_f32_e32 v136, 0xb9800000, v126
	v_fmamk_f32 v139, v126, 0xb9800000, v139
	v_fmac_f32_e32 v138, 0xb9800000, v126
	v_pk_add_f32 v[82:83], v[82:83], v[82:83] op_sel_hi:[0,1]
	v_pk_mul_f32 v[104:105], v[138:139], v[138:139]
	v_pk_mul_f32 v[110:111], v[136:137], v[136:137]
	v_fmac_f32_e32 v120, 0xb9800000, v126
	v_pk_mov_b32 v[124:125], v[110:111], v[104:105] op_sel:[1,0]
	v_mov_b32_e32 v111, v105
	v_fmamk_f32 v121, v126, 0xb9800000, v121
	v_fmac_f32_e32 v122, 0xb9800000, v126
	v_mul_f32_e32 v82, v120, v120
	v_pk_add_f32 v[104:105], v[124:125], v[110:111]
	v_fmamk_f32 v123, v126, 0xb9800000, v123
	v_pk_fma_f32 v[110:111], v[120:121], v[120:121], v[82:83] op_sel_hi:[1,1,0]
	v_mul_f32_e32 v82, v122, v122
	v_pk_add_f32 v[104:105], v[104:105], v[104:105] op_sel_hi:[0,1]
	v_pk_fma_f32 v[124:125], v[122:123], v[122:123], v[82:83] op_sel_hi:[1,1,0]
	v_fmamk_f32 v119, v126, 0xb9800000, v119
	v_fmac_f32_e32 v118, 0xb9800000, v126
	v_fmamk_f32 v117, v126, 0xb9800000, v117
	v_fmac_f32_e32 v116, 0xb9800000, v126
	v_mul_f32_e32 v110, v116, v116
	v_mul_f32_e32 v124, v117, v117
	v_mul_f32_e32 v104, v118, v118
	v_mul_f32_e32 v82, v119, v119
	v_pk_add_f32 v[110:111], v[110:111], v[124:125]
	v_pk_add_f32 v[82:83], v[104:105], v[82:83]
	s_nop 0
	v_pk_add_f32 v[82:83], v[110:111], v[82:83]
	s_nop 0
	v_add_f32_e32 v82, v82, v83
	ds_bpermute_b32 v83, v185, v82
	s_waitcnt lgkmcnt(0)
	v_add_f32_e32 v82, v82, v83
	ds_bpermute_b32 v83, v190, v82
	s_waitcnt lgkmcnt(0)
	v_add_f32_e32 v82, v82, v83
	ds_bpermute_b32 v83, v191, v82
	s_waitcnt lgkmcnt(0)
	v_add_f32_e32 v82, v82, v83
	ds_bpermute_b32 v83, v192, v82
	s_waitcnt lgkmcnt(0)
	v_add_f32_e32 v82, v82, v83
	ds_bpermute_b32 v83, v193, v82
	s_waitcnt lgkmcnt(0)
	v_add_f32_e32 v82, v82, v83
	ds_bpermute_b32 v83, v194, v82
	s_waitcnt lgkmcnt(0)
	v_add_f32_e32 v82, v82, v83
	v_fmamk_f32 v82, v82, 0x39800000, v179
	v_mul_f32_e32 v83, 0x4f800000, v82
	v_cmp_gt_f32_e32 vcc, s48, v82
	s_nop 1
	v_cndmask_b32_e32 v82, v82, v83, vcc
	v_sqrt_f32_e32 v83, v82
	s_nop 0
	v_add_u32_e32 v104, -1, v83
	v_fma_f32 v105, -v104, v83, v82
	v_cmp_ge_f32_e64 s[0:1], 0, v105
	v_add_u32_e32 v105, 1, v83
	s_nop 0
	v_cndmask_b32_e64 v104, v83, v104, s[0:1]
	v_fma_f32 v83, -v105, v83, v82
	v_cmp_lt_f32_e64 s[0:1], 0, v83
	s_nop 1
	v_cndmask_b32_e64 v83, v104, v105, s[0:1]
	v_mul_f32_e32 v104, 0x37800000, v83
	v_cndmask_b32_e32 v83, v83, v104, vcc
	v_cmp_class_f32_e32 vcc, v82, v237
	s_nop 1
	v_cndmask_b32_e32 v82, v83, v82, vcc
	v_div_scale_f32 v83, s[0:1], v82, v82, 1.0
	v_rcp_f32_e32 v104, v83
	s_lshl_b64 s[0:1], s[24:25], 12
	s_and_b64 s[24:25], s[26:27], exec
	s_cselect_b32 s2, 0, s2
	v_fma_f32 v105, -v83, v104, 1.0
	v_fmac_f32_e32 v104, v105, v104
	v_div_scale_f32 v105, vcc, 1.0, v82, 1.0
	v_mul_f32_e32 v110, v105, v104
	v_fma_f32 v111, -v83, v110, v105
	v_fmac_f32_e32 v110, v111, v104
	v_fma_f32 v83, -v83, v110, v105
	v_div_fmas_f32 v83, v83, v104, v110
	v_div_fixup_f32 v82, v83, v82, 1.0
	v_add_u32_e32 v83, s2, v236
	ds_read_b128 v[124:127], v83 offset:49152
	ds_read_b128 v[186:189], v83 offset:50176
	ds_read_b128 v[182:185], v83 offset:32768
	ds_read_b128 v[190:193], v83 offset:33792
	v_pk_mul_f32 v[84:85], v[84:85], v[82:83] op_sel_hi:[1,0]
	s_waitcnt lgkmcnt(3)
	v_pk_add_f32 v[110:111], v[124:125], 1.0 op_sel_hi:[1,0]
	v_pk_mul_f32 v[78:79], v[78:79], v[82:83] op_sel_hi:[1,0]
	s_waitcnt lgkmcnt(1)
	v_pk_fma_f32 v[84:85], v[110:111], v[84:85], v[182:183]
	v_mov_b32_e32 v110, v181
	v_cvt_pk_fp8_f32 v110, v84, v85
	v_pk_mul_f32 v[84:85], v[86:87], v[82:83] op_sel_hi:[1,0]
	v_pk_add_f32 v[86:87], v[126:127], 1.0 op_sel_hi:[1,0]
	v_mov_b32_e32 v111, v181
	v_pk_fma_f32 v[84:85], v[86:87], v[84:85], v[184:185]
	v_pk_mul_f32 v[86:87], v[94:95], v[82:83] op_sel_hi:[1,0]
	v_cvt_pk_fp8_f32 v110, v84, v85 op_sel:[0,0,1]
	v_pk_mul_f32 v[84:85], v[92:93], v[82:83] op_sel_hi:[1,0]
	v_pk_add_f32 v[92:93], v[186:187], 1.0 op_sel_hi:[1,0]
	ds_read_b128 v[124:127], v83 offset:52224
	s_waitcnt lgkmcnt(1)
	v_pk_fma_f32 v[84:85], v[92:93], v[84:85], v[190:191]
	ds_read_b128 v[182:185], v83 offset:35840
	v_cvt_pk_fp8_f32 v111, v84, v85
	v_pk_add_f32 v[84:85], v[188:189], 1.0 op_sel_hi:[1,0]
	v_pk_mul_f32 v[74:75], v[74:75], v[82:83] op_sel_hi:[1,0]
	v_pk_fma_f32 v[92:93], v[84:85], v[86:87], v[192:193]
	ds_read_b128 v[84:87], v83 offset:51200
	v_cvt_pk_fp8_f32 v111, v92, v93 op_sel:[0,0,1]
	ds_read_b128 v[92:95], v83 offset:34816
	v_lshl_add_u64 v[104:105], v[176:177], 0, s[0:1]
	v_pk_mul_f32 v[70:71], v[70:71], v[82:83] op_sel_hi:[1,0]
	s_waitcnt lgkmcnt(1)
	v_pk_add_f32 v[84:85], v[84:85], 1.0 op_sel_hi:[1,0]
	v_pk_mul_f32 v[88:89], v[88:89], v[82:83] op_sel_hi:[1,0]
	s_waitcnt lgkmcnt(0)
	v_pk_fma_f32 v[78:79], v[84:85], v[78:79], v[92:93]
	v_mov_b32_e32 v84, v181
	v_cvt_pk_fp8_f32 v84, v78, v79
	v_pk_mul_f32 v[78:79], v[80:81], v[82:83] op_sel_hi:[1,0]
	v_pk_add_f32 v[80:81], v[86:87], 1.0 op_sel_hi:[1,0]
	v_pk_mul_f32 v[66:67], v[66:67], v[82:83] op_sel_hi:[1,0]
	v_pk_fma_f32 v[78:79], v[80:81], v[78:79], v[94:95]
	s_add_u32 s14, s14, s34
	v_cvt_pk_fp8_f32 v84, v78, v79 op_sel:[0,0,1]
	v_pk_add_f32 v[78:79], v[124:125], 1.0 op_sel_hi:[1,0]
	s_addc_u32 s15, s15, s35
	v_pk_fma_f32 v[74:75], v[78:79], v[74:75], v[182:183]
	v_mov_b32_e32 v78, v181
	v_cvt_pk_fp8_f32 v78, v74, v75
	v_pk_mul_f32 v[74:75], v[76:77], v[82:83] op_sel_hi:[1,0]
	v_pk_add_f32 v[76:77], v[126:127], 1.0 op_sel_hi:[1,0]
	s_add_u32 s4, s4, s6
	v_pk_fma_f32 v[74:75], v[76:77], v[74:75], v[184:185]
	s_addc_u32 s5, s5, s7
	v_cvt_pk_fp8_f32 v78, v74, v75 op_sel:[0,0,1]
	global_store_dword v[104:105], v110, off sc1
	global_store_dword v[104:105], v111, off offset:256 sc1
	global_store_dword v[104:105], v84, off offset:512 sc1
	global_store_dword v[104:105], v78, off offset:768 sc1
	ds_read_b128 v[74:77], v83 offset:53248
	ds_read_b128 v[78:81], v83 offset:36864
	ds_read_b128 v[84:87], v83 offset:54272
	ds_read_b128 v[92:95], v83 offset:37888
	v_mov_b32_e32 v110, v181
	s_waitcnt lgkmcnt(3)
	v_pk_add_f32 v[74:75], v[74:75], 1.0 op_sel_hi:[1,0]
	s_add_i32 s19, s19, s44
	s_waitcnt lgkmcnt(2)
	v_pk_fma_f32 v[70:71], v[74:75], v[70:71], v[78:79]
	s_waitcnt lgkmcnt(1)
	v_pk_add_f32 v[74:75], v[84:85], 1.0 op_sel_hi:[1,0]
	v_cvt_pk_fp8_f32 v110, v70, v71
	v_pk_mul_f32 v[70:71], v[72:73], v[82:83] op_sel_hi:[1,0]
	v_pk_add_f32 v[72:73], v[76:77], 1.0 op_sel_hi:[1,0]
	s_andn2_b64 vcc, exec, s[38:39]
	v_pk_fma_f32 v[70:71], v[72:73], v[70:71], v[80:81]
	v_pk_mul_f32 v[72:73], v[114:115], v[82:83] op_sel_hi:[1,0]
	v_cvt_pk_fp8_f32 v110, v70, v71 op_sel:[0,0,1]
	v_pk_mul_f32 v[70:71], v[112:113], v[82:83] op_sel_hi:[1,0]
	ds_read_b128 v[78:81], v83 offset:56320
	s_waitcnt lgkmcnt(1)
	v_pk_fma_f32 v[70:71], v[74:75], v[70:71], v[92:93]
	v_mov_b32_e32 v92, v181
	v_cvt_pk_fp8_f32 v92, v70, v71
	v_pk_add_f32 v[70:71], v[86:87], 1.0 op_sel_hi:[1,0]
	ds_read_b128 v[84:87], v83 offset:39936
	v_pk_fma_f32 v[74:75], v[70:71], v[72:73], v[94:95]
	ds_read_b128 v[70:73], v83 offset:55296
	v_cvt_pk_fp8_f32 v92, v74, v75 op_sel:[0,0,1]
	ds_read_b128 v[74:77], v83 offset:38912
	s_mov_b32 s24, s36
	s_waitcnt lgkmcnt(1)
	v_pk_add_f32 v[70:71], v[70:71], 1.0 op_sel_hi:[1,0]
	v_pk_add_f32 v[72:73], v[72:73], 1.0 op_sel_hi:[1,0]
	s_waitcnt lgkmcnt(0)
	v_pk_fma_f32 v[70:71], v[88:89], v[70:71], v[74:75]
	v_mov_b32_e32 v74, v181
	v_cvt_pk_fp8_f32 v74, v70, v71
	v_pk_mul_f32 v[70:71], v[90:91], v[82:83] op_sel_hi:[1,0]
	v_mov_b32_e32 v75, v181
	v_pk_fma_f32 v[70:71], v[70:71], v[72:73], v[76:77]
	v_pk_add_f32 v[72:73], v[78:79], 1.0 op_sel_hi:[1,0]
	v_cvt_pk_fp8_f32 v74, v70, v71 op_sel:[0,0,1]
	v_pk_mul_f32 v[70:71], v[96:97], v[82:83] op_sel_hi:[1,0]
	v_mov_b32_e32 v88, v181
	v_pk_fma_f32 v[70:71], v[70:71], v[72:73], v[84:85]
	v_pk_add_f32 v[72:73], v[80:81], 1.0 op_sel_hi:[1,0]
	v_cvt_pk_fp8_f32 v75, v70, v71
	v_pk_mul_f32 v[70:71], v[98:99], v[82:83] op_sel_hi:[1,0]
	v_mov_b32_e32 v89, v181
	v_pk_fma_f32 v[70:71], v[70:71], v[72:73], v[86:87]
	s_nop 0
	v_cvt_pk_fp8_f32 v75, v70, v71 op_sel:[0,0,1]
	global_store_dword v[104:105], v110, off offset:1024 sc1
	global_store_dword v[104:105], v92, off offset:1280 sc1
	global_store_dword v[104:105], v74, off offset:1536 sc1
	global_store_dword v[104:105], v75, off offset:1792 sc1
	ds_read_b128 v[70:73], v83 offset:57344
	ds_read_b128 v[74:77], v83 offset:40960
	ds_read_b128 v[78:81], v83 offset:58368
	ds_read_b128 v[84:87], v83 offset:41984
	s_waitcnt lgkmcnt(3)
	v_pk_add_f32 v[70:71], v[70:71], 1.0 op_sel_hi:[1,0]
	s_waitcnt lgkmcnt(2)
	v_pk_fma_f32 v[66:67], v[66:67], v[70:71], v[74:75]
	s_waitcnt lgkmcnt(1)
	v_pk_add_f32 v[70:71], v[78:79], 1.0 op_sel_hi:[1,0]
	v_cvt_pk_fp8_f32 v88, v66, v67
	v_pk_mul_f32 v[66:67], v[68:69], v[82:83] op_sel_hi:[1,0]
	v_pk_add_f32 v[68:69], v[72:73], 1.0 op_sel_hi:[1,0]
	s_nop 0
	v_pk_fma_f32 v[66:67], v[66:67], v[68:69], v[76:77]
	v_pk_mul_f32 v[68:69], v[130:131], v[82:83] op_sel_hi:[1,0]
	v_cvt_pk_fp8_f32 v88, v66, v67 op_sel:[0,0,1]
	v_pk_mul_f32 v[66:67], v[128:129], v[82:83] op_sel_hi:[1,0]
	ds_read_b128 v[74:77], v83 offset:60416
	s_waitcnt lgkmcnt(1)
	v_pk_fma_f32 v[66:67], v[66:67], v[70:71], v[84:85]
	v_pk_mul_f32 v[84:85], v[106:107], v[82:83] op_sel_hi:[1,0]
	v_cvt_pk_fp8_f32 v89, v66, v67
	v_pk_add_f32 v[66:67], v[80:81], 1.0 op_sel_hi:[1,0]
	ds_read_b128 v[78:81], v83 offset:44032
	v_pk_fma_f32 v[70:71], v[68:69], v[66:67], v[86:87]
	ds_read_b128 v[66:69], v83 offset:59392
	v_cvt_pk_fp8_f32 v89, v70, v71 op_sel:[0,0,1]
	ds_read_b128 v[70:73], v83 offset:43008
	v_mov_b32_e32 v86, v181
	v_mov_b32_e32 v87, v181
	s_waitcnt lgkmcnt(1)
	v_pk_add_f32 v[66:67], v[66:67], 1.0 op_sel_hi:[1,0]
	v_pk_add_f32 v[68:69], v[68:69], 1.0 op_sel_hi:[1,0]
	s_waitcnt lgkmcnt(0)
	v_pk_fma_f32 v[66:67], v[84:85], v[66:67], v[70:71]
	v_mov_b32_e32 v70, v181
	v_cvt_pk_fp8_f32 v70, v66, v67
	v_pk_mul_f32 v[66:67], v[108:109], v[82:83] op_sel_hi:[1,0]
	v_mov_b32_e32 v71, v181
	v_pk_fma_f32 v[66:67], v[66:67], v[68:69], v[72:73]
	v_pk_add_f32 v[68:69], v[74:75], 1.0 op_sel_hi:[1,0]
	v_cvt_pk_fp8_f32 v70, v66, v67 op_sel:[0,0,1]
	v_pk_mul_f32 v[66:67], v[100:101], v[82:83] op_sel_hi:[1,0]
	v_pk_mul_f32 v[84:85], v[132:133], v[82:83] op_sel_hi:[1,0]
	v_pk_fma_f32 v[66:67], v[66:67], v[68:69], v[78:79]
	v_pk_add_f32 v[68:69], v[76:77], 1.0 op_sel_hi:[1,0]
	v_cvt_pk_fp8_f32 v71, v66, v67
	v_pk_mul_f32 v[66:67], v[102:103], v[82:83] op_sel_hi:[1,0]
	s_nop 0
	v_pk_fma_f32 v[66:67], v[66:67], v[68:69], v[80:81]
	s_nop 0
	v_cvt_pk_fp8_f32 v71, v66, v67 op_sel:[0,0,1]
	global_store_dword v[104:105], v88, off offset:2048 sc1
	global_store_dword v[104:105], v89, off offset:2304 sc1
	global_store_dword v[104:105], v70, off offset:2560 sc1
	global_store_dword v[104:105], v71, off offset:2816 sc1
	ds_read_b128 v[66:69], v83 offset:61440
	ds_read_b128 v[70:73], v83 offset:45056
	ds_read_b128 v[74:77], v83 offset:62464
	ds_read_b128 v[78:81], v83 offset:46080
	s_waitcnt lgkmcnt(3)
	v_pk_add_f32 v[66:67], v[66:67], 1.0 op_sel_hi:[1,0]
	s_waitcnt lgkmcnt(2)
	v_pk_fma_f32 v[66:67], v[84:85], v[66:67], v[70:71]
	v_pk_add_f32 v[68:69], v[68:69], 1.0 op_sel_hi:[1,0]
	v_cvt_pk_fp8_f32 v86, v66, v67
	v_pk_mul_f32 v[66:67], v[134:135], v[82:83] op_sel_hi:[1,0]
	s_waitcnt lgkmcnt(1)
	v_pk_add_f32 v[70:71], v[74:75], 1.0 op_sel_hi:[1,0]
	v_pk_fma_f32 v[66:67], v[66:67], v[68:69], v[72:73]
	v_pk_mul_f32 v[68:69], v[138:139], v[82:83] op_sel_hi:[1,0]
	v_cvt_pk_fp8_f32 v86, v66, v67 op_sel:[0,0,1]
	v_pk_mul_f32 v[66:67], v[136:137], v[82:83] op_sel_hi:[1,0]
	v_pk_mul_f32 v[84:85], v[120:121], v[82:83] op_sel_hi:[1,0]
	s_waitcnt lgkmcnt(0)
	v_pk_fma_f32 v[66:67], v[66:67], v[70:71], v[78:79]
	s_nop 0
	v_cvt_pk_fp8_f32 v87, v66, v67
	v_pk_add_f32 v[66:67], v[76:77], 1.0 op_sel_hi:[1,0]
	ds_read_b128 v[74:77], v83 offset:64512
	v_pk_fma_f32 v[70:71], v[68:69], v[66:67], v[80:81]
	ds_read_b128 v[66:69], v83 offset:63488
	v_cvt_pk_fp8_f32 v87, v70, v71 op_sel:[0,0,1]
	ds_read_b128 v[70:73], v83 offset:47104
	ds_read_b128 v[78:81], v83 offset:48128
	s_waitcnt lgkmcnt(2)
	v_pk_add_f32 v[66:67], v[66:67], 1.0 op_sel_hi:[1,0]
	v_pk_add_f32 v[68:69], v[68:69], 1.0 op_sel_hi:[1,0]
	s_waitcnt lgkmcnt(1)
	v_pk_fma_f32 v[66:67], v[84:85], v[66:67], v[70:71]
	v_mov_b32_e32 v70, v181
	v_cvt_pk_fp8_f32 v70, v66, v67
	v_pk_mul_f32 v[66:67], v[122:123], v[82:83] op_sel_hi:[1,0]
	v_mov_b32_e32 v71, v181
	v_pk_fma_f32 v[66:67], v[66:67], v[68:69], v[72:73]
	v_pk_add_f32 v[68:69], v[74:75], 1.0 op_sel_hi:[1,0]
	v_cvt_pk_fp8_f32 v70, v66, v67 op_sel:[0,0,1]
	v_pk_mul_f32 v[66:67], v[116:117], v[82:83] op_sel_hi:[1,0]
	s_waitcnt lgkmcnt(0)
	v_pk_fma_f32 v[66:67], v[66:67], v[68:69], v[78:79]
	v_pk_add_f32 v[68:69], v[76:77], 1.0 op_sel_hi:[1,0]
	v_cvt_pk_fp8_f32 v71, v66, v67
	v_pk_mul_f32 v[66:67], v[118:119], v[82:83] op_sel_hi:[1,0]
	s_nop 0
	v_pk_fma_f32 v[66:67], v[66:67], v[68:69], v[80:81]
	s_nop 0
	v_cvt_pk_fp8_f32 v71, v66, v67 op_sel:[0,0,1]
	global_store_dword v[104:105], v86, off offset:3072 sc1
	global_store_dword v[104:105], v87, off offset:3328 sc1
	global_store_dword v[104:105], v70, off offset:3584 sc1
	global_store_dword v[104:105], v71, off offset:3840 sc1
	s_cbranch_vccz .LBB0_883
